# v23: v16 plus residual and gate epilogues sum the row's squared-norm partials across the four quarter-waves with v_permlane16_swap / v_permlane32_swap instead of two ds_bpermute round trips per row gr
# speedup vs baseline: 1.0001x; 1.0001x over previous
; __device__ __forceinline__ void publish_row_p(const f32x4 (&xn)[2][2], bf16_t* xbrow, float* ssrow, int fq, int lane) {
;     ...
;     for (int bj = 0; bj < 2; ++bj) { const f32x4 v0 = xn[bj][0], v1 = xn[bj][1];
;         q += ((v0[0] * v0[0] + v0[1] * v0[1]) + (v0[2] * v0[2] + v0[3] * v0[3])) + ((v1[0] * v1[0] + v1[1] * v1[1]) + (v1[2] * v1[2] + v1[3] * v1[3]));
;         u32x4 w; w.x = cvt_pk_bf16(v0[0], v0[1]); w.y = cvt_pk_bf16(v0[2], v0[3]); w.z = cvt_pk_bf16(v1[0], v1[1]); w.w = cvt_pk_bf16(v1[2], v1[3]); *(u32x4*)(xbrow + bj * HALF) = w; }
;     q += __int_as_float(__builtin_amdgcn_ds_bpermute((lane ^ 16) << 2, __float_as_int(q)));
;     q += __int_as_float(__builtin_amdgcn_ds_bpermute((lane ^ 32) << 2, __float_as_int(q)));
;     if (fq == 0) *ssrow = q;
;     __device__ __forceinline__ void operator()(const f32x4 (&acc)[2][2][4][2], const Unit& u, int wr, int wc, int fr, int fq) const {
;     ...
;         for (int bj = 0; bj < 2; ++bj) { const size_t o_ = (size_t)row0 * ldc + col0 + bj * HALF; xnext[bj] = *(const u32x4*)(Sin + o_); tnext[bj] = *(const u32x4*)(T + o_); }
; #pragma unroll
;         for (int r = 0; r < 8; ++r) { const int ai = r >> 2, m = r & 3; const int row = row0 + ai * HALF + m * 16; const size_t off = (size_t)row * ldc + col0; const float rsc = tab[wr * 64 + fr + ai * HALF + m * 16];
; #pragma unroll
;             for (int bj = 0; bj < 2; ++bj) { xv[bj] = xnext[bj]; tv[bj] = tnext[bj]; }
;             if (r < 7) { const int rown = row0 + ((r + 1) >> 2) * HALF + ((r + 1) & 3) * 16;
; #pragma unroll
;                 for (int bj = 0; bj < 2; ++bj) { const size_t o_ = (size_t)rown * ldc + col0 + bj * HALF; xnext[bj] = *(const u32x4*)(Sin + o_); tnext[bj] = *(const u32x4*)(T + o_); } }
;             f32x4 xn[2][2];
; #pragma unroll
;             for (int bj = 0; bj < 2; ++bj) { f32x4 xa, xb, ta, tb; unpack8(xv[bj], xa, xb); unpack8(tv[bj], ta, tb);
;                 const f32x4 a0 = acc[ai][bj][m][0] * rsc, a1 = acc[ai][bj][m][1] * rsc;
; #pragma unroll
;                 for (int e_ = 0; e_ < 4; ++e_) { xn[bj][0][e_] = xa[e_] + __builtin_amdgcn_rcpf(1.0f + __expf(-a0[e_])) * ta[e_]; xn[bj][1][e_] = xb[e_] + __builtin_amdgcn_rcpf(1.0f + __expf(-a1[e_])) * tb[e_]; } }
;             publish_row_p(xn, Sout + off, ss + (size_t)row * 32 + u.pn * 4 + wc, fq, lane); }
.LBB0_225:
	v_and_b32_e32 v131, 15, v130
	s_add_i32 s3, s3, s90
	v_or_b32_e32 v160, s3, v131
	s_lshl_b32 s3, s34, 8
	v_lshrrev_b32_e32 v132, 1, v130
	s_or_b32 s3, s3, s91
	v_and_b32_e32 v132, 56, v132
	v_add_u32_e32 v158, s3, v132
	v_ashrrev_i32_e32 v161, 31, v160
	v_lshlrev_b64 v[132:133], 11, v[160:161]
	v_ashrrev_i32_e32 v159, 31, v158
	v_lshl_add_u64 v[132:133], v[132:133], 0, v[158:159]
	v_lshlrev_b64 v[132:133], 1, v[132:133]
	v_lshl_add_u64 v[138:139], s[10:11], 0, v[132:133]
	v_lshl_add_u64 v[132:133], s[8:9], 0, v[132:133]
	s_waitcnt lgkmcnt(0)
	global_load_dwordx4 v[134:137], v[138:139], off
	global_load_dwordx4 v[180:183], v[138:139], off offset:256
	global_load_dwordx4 v[176:179], v[132:133], off
	global_load_dwordx4 v[184:187], v[132:133], off offset:256
	v_lshl_add_u32 v174, v131, 2, s65
	v_or_b32_e32 v162, 16, v160
	ds_read_b32 v168, v174
	v_ashrrev_i32_e32 v163, 31, v162
	v_lshlrev_b64 v[166:167], 11, v[162:163]
	v_cmp_gt_u32_e32 vcc, 16, v130
	v_lshl_add_u64 v[130:131], v[166:167], 0, v[158:159]
	v_lshlrev_b64 v[130:131], 1, v[130:131]
	v_lshl_add_u64 v[132:133], s[10:11], 0, v[130:131]
	v_lshl_add_u64 v[164:165], s[8:9], 0, v[130:131]
	s_waitcnt lgkmcnt(0)
	v_mul_f32_e64 v169, v126, -v168
	v_mul_f32_e64 v175, v127, -v168
	v_mul_f32_e64 v188, v128, -v168
	v_mul_f32_e64 v189, v129, -v168
	global_load_dwordx4 v[142:145], v[132:133], off
	s_nop 0
	global_load_dwordx4 v[130:133], v[132:133], off offset:256
	s_nop 0
	global_load_dwordx4 v[138:141], v[164:165], off
	global_load_dwordx4 v[126:129], v[164:165], off offset:256
	v_mul_f32_e64 v122, v122, -v168
	v_mul_f32_e32 v122, 0x3fb8aa3b, v122
	v_exp_f32_e32 v122, v122
	v_mul_f32_e64 v123, v123, -v168
	v_mul_f32_e32 v123, 0x3fb8aa3b, v123
	v_exp_f32_e32 v123, v123
	v_add_f32_e32 v122, 1.0, v122
	v_rcp_f32_e32 v122, v122
	v_mul_f32_e64 v124, v124, -v168
	v_mul_f32_e32 v164, 0x3fb8aa3b, v169
	v_mul_f32_e32 v124, 0x3fb8aa3b, v124
	v_mul_f32_e64 v114, v114, -v168
	v_exp_f32_e32 v164, v164
	v_exp_f32_e32 v124, v124
	v_add_f32_e32 v123, 1.0, v123
	v_mul_f32_e32 v114, 0x3fb8aa3b, v114
	v_rcp_f32_e32 v123, v123
	v_exp_f32_e32 v114, v114
	v_add_f32_e32 v164, 1.0, v164
	v_add_f32_e32 v124, 1.0, v124
	v_mul_f32_e64 v115, v115, -v168
	v_mul_f32_e32 v165, 0x3fb8aa3b, v175
	v_mul_f32_e32 v175, 0x3fb8aa3b, v189
	v_rcp_f32_e32 v164, v164
	v_add_f32_e32 v114, 1.0, v114
	v_mul_f32_e32 v115, 0x3fb8aa3b, v115
	v_exp_f32_e32 v165, v165
	v_exp_f32_e32 v175, v175
	v_rcp_f32_e32 v114, v114
	v_exp_f32_e32 v115, v115
	v_mul_f32_e32 v169, 0x3fb8aa3b, v188
	v_add_f32_e32 v165, 1.0, v165
	v_mul_f32_e64 v116, v116, -v168
	v_rcp_f32_e32 v165, v165
	v_mul_f32_e32 v116, 0x3fb8aa3b, v116
	v_exp_f32_e32 v116, v116
	v_exp_f32_e32 v169, v169
	v_mul_f32_e64 v119, v119, -v168
	v_mul_f32_e64 v118, v118, -v168
	v_mul_f32_e32 v119, 0x3fb8aa3b, v119
	v_mul_f32_e64 v117, v117, -v168
	v_mul_f32_e32 v118, 0x3fb8aa3b, v118
	v_exp_f32_e32 v119, v119
	v_mul_f32_e32 v117, 0x3fb8aa3b, v117
	v_exp_f32_e32 v118, v118
	v_exp_f32_e32 v117, v117
	v_add_f32_e32 v169, 1.0, v169
	v_rcp_f32_e32 v169, v169
	v_add_f32_e32 v119, 1.0, v119
	v_add_f32_e32 v118, 1.0, v118
	v_rcp_f32_e32 v119, v119
	v_add_f32_e32 v117, 1.0, v117
	v_rcp_f32_e32 v118, v118
	v_rcp_f32_e32 v117, v117
	v_xor_b32_e32 v173, 64, v0
	v_xor_b32_e32 v0, 0x80, v0
	s_lshl_b32 s34, s34, 2
	s_ashr_i32 s35, s34, 31
	s_waitcnt vmcnt(0)
	v_lshlrev_b32_e32 v190, 16, v136
	v_and_b32_e32 v136, 0xffff0000, v136
	v_lshlrev_b32_e32 v194, 16, v178
	v_fmac_f32_e32 v190, v122, v194
	v_mul_f32_e64 v122, v125, -v168
	v_mul_f32_e32 v122, 0x3fb8aa3b, v122
	v_exp_f32_e32 v122, v122
	v_and_b32_e32 v178, 0xffff0000, v178
	v_fmac_f32_e32 v136, v123, v178
	v_rcp_f32_e32 v123, v124
	v_add_f32_e32 v122, 1.0, v122
	v_rcp_f32_e32 v122, v122
	v_lshlrev_b32_e32 v188, 16, v134
	v_lshlrev_b32_e32 v191, 16, v137
	v_and_b32_e32 v137, 0xffff0000, v137
	v_lshlrev_b32_e32 v192, 16, v176
	v_lshlrev_b32_e32 v195, 16, v179
	v_and_b32_e32 v179, 0xffff0000, v179
	v_fmac_f32_e32 v188, v164, v192
	v_fmac_f32_e32 v191, v123, v195
	v_fmac_f32_e32 v137, v122, v179
	v_lshlrev_b32_e32 v122, 16, v180
	v_and_b32_e32 v123, 0xffff0000, v180
	v_lshlrev_b32_e32 v164, 16, v182
	v_lshlrev_b32_e32 v180, 16, v186
	v_add_f32_e32 v124, 1.0, v175
	v_fmac_f32_e32 v164, v114, v180
	v_add_f32_e32 v114, 1.0, v115
	v_mul_f32_e64 v115, v120, -v168
	v_rcp_f32_e32 v124, v124
	v_mul_f32_e32 v115, 0x3fb8aa3b, v115
	v_rcp_f32_e32 v114, v114
	v_exp_f32_e32 v115, v115
	v_and_b32_e32 v134, 0xffff0000, v134
	v_lshlrev_b32_e32 v189, 16, v135
	v_and_b32_e32 v135, 0xffff0000, v135
	v_and_b32_e32 v176, 0xffff0000, v176
	v_lshlrev_b32_e32 v193, 16, v177
	v_and_b32_e32 v177, 0xffff0000, v177
	v_fmac_f32_e32 v134, v165, v176
	v_fmac_f32_e32 v135, v124, v177
	v_lshlrev_b32_e32 v124, 16, v181
	v_and_b32_e32 v125, 0xffff0000, v181
	v_and_b32_e32 v165, 0xffff0000, v182
	v_and_b32_e32 v181, 0xffff0000, v186
	v_fmac_f32_e32 v165, v114, v181
	v_add_f32_e32 v114, 1.0, v115
	v_add_f32_e32 v115, 1.0, v116
	v_mul_f32_e64 v116, v121, -v168
	v_mul_f32_e32 v116, 0x3fb8aa3b, v116
	v_exp_f32_e32 v116, v116
	v_rcp_f32_e32 v114, v114
	v_rcp_f32_e32 v115, v115
	v_fmac_f32_e32 v189, v169, v193
	v_add_f32_e32 v116, 1.0, v116
	v_rcp_f32_e32 v116, v116
	v_lshlrev_b32_e32 v169, 16, v183
	v_lshlrev_b32_e32 v178, 16, v185
	v_lshlrev_b32_e32 v182, 16, v187
	v_and_b32_e32 v177, 0xffff0000, v184
	v_and_b32_e32 v179, 0xffff0000, v185
	v_fmac_f32_e32 v124, v114, v178
	v_fmac_f32_e32 v169, v115, v182
	v_lshlrev_b64 v[114:115], 12, v[160:161]
	v_and_b32_e32 v175, 0xffff0000, v183
	v_lshlrev_b32_e32 v176, 16, v184
	v_and_b32_e32 v183, 0xffff0000, v187
	v_fmac_f32_e32 v123, v119, v177
	v_fmac_f32_e32 v125, v116, v179
	v_lshl_add_u64 v[114:115], s[14:15], 0, v[114:115]
	v_fmac_f32_e32 v122, v118, v176
	v_fmac_f32_e32 v175, v117, v183
	v_lshl_add_u64 v[120:121], v[158:159], 1, v[114:115]
	v_mul_f32_e32 v114, v134, v134
	v_mul_f32_e32 v115, v135, v135
	v_mul_f32_e32 v117, v123, v123
	v_mul_f32_e32 v118, v125, v125
	v_fmac_f32_e32 v114, v188, v188
	v_fmac_f32_e32 v115, v189, v189
	v_fmac_f32_e32 v117, v122, v122
	v_fmac_f32_e32 v118, v124, v124
	v_add_f32_e32 v114, v114, v115
	v_mul_f32_e32 v115, v136, v136
	v_mul_f32_e32 v116, v137, v137
	v_add_f32_e32 v117, v117, v118
	v_mul_f32_e32 v118, v165, v165
	v_mul_f32_e32 v119, v175, v175
	v_fmac_f32_e32 v115, v190, v190
	v_fmac_f32_e32 v116, v191, v191
	v_fmac_f32_e32 v118, v164, v164
	v_fmac_f32_e32 v119, v169, v169
	v_add_f32_e32 v115, v115, v116
	v_add_f32_e32 v118, v118, v119
	v_add_f32_e32 v116, v114, v115
	v_add_f32_e32 v117, v117, v118
	v_add_f32_e32 v118, v116, v117
	s_nop 1
	v_mov_b32_e32 v119, v118
	s_nop 1
	v_permlane16_swap_b32_e32 v118, v119
	v_cvt_pk_bf16_f32 v114, v188, v134
	v_cvt_pk_bf16_f32 v115, v189, v135
	v_cvt_pk_bf16_f32 v116, v190, v136
	v_cvt_pk_bf16_f32 v117, v191, v137
	global_store_dwordx4 v[120:121], v[114:117], off
	s_waitcnt lgkmcnt(0)
; __device__ __forceinline__ unsigned cvt_pk_bf16(float lo, float hi) { unsigned r; asm volatile("v_cvt_pk_bf16_f32 %0, %1, %2" : "=v"(r) : "v"(lo), "v"(hi)); return r; }
; __device__ __forceinline__ void publish_row_p(const f32x4 (&xn)[2][2], bf16_t* xbrow, float* ssrow, int fq, int lane) {
;     ...
;     for (int bj = 0; bj < 2; ++bj) { const f32x4 v0 = xn[bj][0], v1 = xn[bj][1];
;         q += ((v0[0] * v0[0] + v0[1] * v0[1]) + (v0[2] * v0[2] + v0[3] * v0[3])) + ((v1[0] * v1[0] + v1[1] * v1[1]) + (v1[2] * v1[2] + v1[3] * v1[3]));
;         u32x4 w; w.x = cvt_pk_bf16(v0[0], v0[1]); w.y = cvt_pk_bf16(v0[2], v0[3]); w.z = cvt_pk_bf16(v1[0], v1[1]); w.w = cvt_pk_bf16(v1[2], v1[3]); *(u32x4*)(xbrow + bj * HALF) = w; }
;     q += __int_as_float(__builtin_amdgcn_ds_bpermute((lane ^ 16) << 2, __float_as_int(q)));
;     q += __int_as_float(__builtin_amdgcn_ds_bpermute((lane ^ 32) << 2, __float_as_int(q)));
;     if (fq == 0) *ssrow = q;
;     __device__ __forceinline__ void operator()(const f32x4 (&acc)[2][2][4][2], const Unit& u, int wr, int wc, int fr, int fq) const {
;     ...
;         for (int r = 0; r < 8; ++r) { const int ai = r >> 2, m = r & 3; const int row = row0 + ai * HALF + m * 16; const size_t off = (size_t)row * ldc + col0; const float rsc = tab[wr * 64 + fr + ai * HALF + m * 16];
; #pragma unroll
;             for (int bj = 0; bj < 2; ++bj) { xv[bj] = xnext[bj]; tv[bj] = tnext[bj]; }
;             if (r < 7) { const int rown = row0 + ((r + 1) >> 2) * HALF + ((r + 1) & 3) * 16;
; #pragma unroll
;                 for (int bj = 0; bj < 2; ++bj) { const size_t o_ = (size_t)rown * ldc + col0 + bj * HALF; xnext[bj] = *(const u32x4*)(Sin + o_); tnext[bj] = *(const u32x4*)(T + o_); } }
;             f32x4 xn[2][2];
; #pragma unroll
;             for (int bj = 0; bj < 2; ++bj) { f32x4 xa, xb, ta, tb; unpack8(xv[bj], xa, xb); unpack8(tv[bj], ta, tb);
;                 const f32x4 a0 = acc[ai][bj][m][0] * rsc, a1 = acc[ai][bj][m][1] * rsc;
; #pragma unroll
;                 for (int e_ = 0; e_ < 4; ++e_) { xn[bj][0][e_] = xa[e_] + __builtin_amdgcn_rcpf(1.0f + __expf(-a0[e_])) * ta[e_]; xn[bj][1][e_] = xb[e_] + __builtin_amdgcn_rcpf(1.0f + __expf(-a1[e_])) * tb[e_]; } }
;             publish_row_p(xn, Sout + off, ss + (size_t)row * 32 + u.pn * 4 + wc, fq, lane); }
	s_nop 0
	v_add_f32_e32 v114, v118, v119
	s_nop 1
	v_mov_b32_e32 v115, v114
	s_nop 1
	v_permlane32_swap_b32_e32 v114, v115
	v_cvt_pk_bf16_f32 v116, v122, v123
	v_cvt_pk_bf16_f32 v117, v124, v125
	v_cvt_pk_bf16_f32 v118, v164, v165
	v_cvt_pk_bf16_f32 v119, v169, v175
	global_store_dwordx4 v[120:121], v[116:119], off offset:256
	s_and_saveexec_b64 s[36:37], vcc
	s_cbranch_execz .LBB0_227
	s_waitcnt lgkmcnt(0)
	v_add_f32_e32 v116, v114, v115
	v_lshlrev_b64 v[114:115], 7, v[160:161]
	v_lshl_add_u64 v[114:115], s[16:17], 0, v[114:115]
	v_lshl_add_u64 v[114:115], s[34:35], 2, v[114:115]
	s_lshl_b32 s52, s84, 2
	v_lshl_add_u64 v[114:115], v[114:115], 0, s[52:53]
	global_store_dword v[114:115], v116, off
.LBB0_227:
	s_or_b64 exec, exec, s[36:37]
	v_or_b32_e32 v164, 32, v160
	v_ashrrev_i32_e32 v165, 31, v164
	v_lshlrev_b64 v[168:169], 11, v[164:165]
	s_waitcnt lgkmcnt(0)
	v_lshl_add_u64 v[114:115], v[168:169], 0, v[158:159]
	v_lshlrev_b64 v[114:115], 1, v[114:115]
	v_lshl_add_u64 v[116:117], s[10:11], 0, v[114:115]
	v_lshl_add_u64 v[114:115], s[8:9], 0, v[114:115]
	ds_read_b32 v161, v174 offset:64
	global_load_dwordx4 v[134:137], v[116:117], off
	global_load_dwordx4 v[118:121], v[116:117], off offset:256
	global_load_dwordx4 v[122:125], v[114:115], off
	s_nop 0
	global_load_dwordx4 v[114:117], v[114:115], off offset:256
	v_lshlrev_b32_e32 v175, 16, v142
	v_and_b32_e32 v142, 0xffff0000, v142
	v_lshlrev_b32_e32 v177, 16, v144
	s_waitcnt lgkmcnt(0)
	v_mul_f32_e64 v110, v110, -v161
	v_mul_f32_e64 v106, v106, -v161
	v_mul_f32_e64 v111, v111, -v161
	v_mul_f32_e32 v110, 0x3fb8aa3b, v110
	v_mul_f32_e32 v106, 0x3fb8aa3b, v106
	v_mul_f32_e32 v111, 0x3fb8aa3b, v111
	v_mul_f32_e64 v98, v98, -v161
	v_exp_f32_e32 v110, v110
	v_exp_f32_e32 v106, v106
	v_exp_f32_e32 v111, v111
	v_mul_f32_e32 v98, 0x3fb8aa3b, v98
	v_exp_f32_e32 v98, v98
	v_mul_f32_e64 v107, v107, -v161
	v_add_f32_e32 v110, 1.0, v110
	v_add_f32_e32 v106, 1.0, v106
	v_add_f32_e32 v111, 1.0, v111
	v_mul_f32_e32 v107, 0x3fb8aa3b, v107
	v_mul_f32_e64 v99, v99, -v161
	v_rcp_f32_e32 v110, v110
	v_rcp_f32_e32 v106, v106
	v_rcp_f32_e32 v111, v111
	v_exp_f32_e32 v107, v107
	v_add_f32_e32 v98, 1.0, v98
	v_mul_f32_e32 v99, 0x3fb8aa3b, v99
	v_rcp_f32_e32 v98, v98
	v_exp_f32_e32 v99, v99
	v_lshlrev_b32_e32 v179, 16, v138
	v_and_b32_e32 v138, 0xffff0000, v138
	v_lshlrev_b32_e32 v181, 16, v140
	v_fmac_f32_e32 v175, v110, v179
	v_fmac_f32_e32 v177, v106, v181
	v_fmac_f32_e32 v142, v111, v138
	v_add_f32_e32 v106, 1.0, v107
	v_mul_f32_e64 v107, v112, -v161
	v_mul_f32_e64 v108, v108, -v161
	v_lshlrev_b32_e32 v110, 16, v132
	v_and_b32_e32 v111, 0xffff0000, v132
	v_lshlrev_b32_e32 v132, 16, v128
	v_mul_f32_e32 v107, 0x3fb8aa3b, v107
	v_mul_f32_e32 v108, 0x3fb8aa3b, v108
	v_fmac_f32_e32 v110, v98, v132
	v_add_f32_e32 v98, 1.0, v99
	v_mul_f32_e64 v99, v104, -v161
	v_mul_f32_e64 v100, v100, -v161
	v_rcp_f32_e32 v106, v106
	v_exp_f32_e32 v107, v107
	v_exp_f32_e32 v108, v108
	v_mul_f32_e32 v99, 0x3fb8aa3b, v99
	v_mul_f32_e32 v100, 0x3fb8aa3b, v100
	v_rcp_f32_e32 v98, v98
	v_exp_f32_e32 v99, v99
	v_exp_f32_e32 v100, v100
	v_and_b32_e32 v144, 0xffff0000, v144
	v_and_b32_e32 v140, 0xffff0000, v140
	v_fmac_f32_e32 v144, v106, v140
	v_add_f32_e32 v106, 1.0, v107
	v_add_f32_e32 v107, 1.0, v108
	v_mul_f32_e64 v108, v113, -v161
	v_mul_f32_e64 v109, v109, -v161
	v_and_b32_e32 v128, 0xffff0000, v128
	v_mul_f32_e32 v108, 0x3fb8aa3b, v108
	v_mul_f32_e32 v109, 0x3fb8aa3b, v109
	v_mul_f32_e64 v103, v103, -v161
	v_fmac_f32_e32 v111, v98, v128
	v_add_f32_e32 v98, 1.0, v99
	v_add_f32_e32 v99, 1.0, v100
	v_mul_f32_e64 v100, v105, -v161
	v_exp_f32_e32 v108, v108
	v_exp_f32_e32 v109, v109
	v_mul_f32_e64 v102, v102, -v161
	v_mul_f32_e32 v103, 0x3fb8aa3b, v103
	v_mul_f32_e32 v100, 0x3fb8aa3b, v100
	v_mul_f32_e64 v101, v101, -v161
	v_mul_f32_e32 v102, 0x3fb8aa3b, v102
	v_exp_f32_e32 v103, v103
	v_exp_f32_e32 v100, v100
	v_mul_f32_e32 v101, 0x3fb8aa3b, v101
	v_exp_f32_e32 v102, v102
	v_exp_f32_e32 v101, v101
	v_add_f32_e32 v108, 1.0, v108
	v_add_f32_e32 v109, 1.0, v109
	v_rcp_f32_e32 v106, v106
	v_rcp_f32_e32 v107, v107
	v_rcp_f32_e32 v108, v108
	v_rcp_f32_e32 v109, v109
	v_add_f32_e32 v103, 1.0, v103
	v_add_f32_e32 v100, 1.0, v100
	v_add_f32_e32 v102, 1.0, v102
	v_rcp_f32_e32 v103, v103
	v_rcp_f32_e32 v98, v98
	v_rcp_f32_e32 v99, v99
	v_rcp_f32_e32 v100, v100
	v_add_f32_e32 v101, 1.0, v101
	v_rcp_f32_e32 v102, v102
	v_rcp_f32_e32 v101, v101
	v_lshlrev_b32_e32 v176, 16, v143
	v_and_b32_e32 v143, 0xffff0000, v143
	v_lshlrev_b32_e32 v178, 16, v145
	v_and_b32_e32 v145, 0xffff0000, v145
	v_lshlrev_b32_e32 v180, 16, v139
	v_and_b32_e32 v139, 0xffff0000, v139
	v_lshlrev_b32_e32 v182, 16, v141
	v_and_b32_e32 v141, 0xffff0000, v141
	v_fmac_f32_e32 v176, v106, v180
	v_fmac_f32_e32 v178, v107, v182
	v_fmac_f32_e32 v143, v108, v139
	v_fmac_f32_e32 v145, v109, v141
	v_lshlrev_b32_e32 v106, 16, v130
	v_and_b32_e32 v107, 0xffff0000, v130
	v_lshlrev_b32_e32 v108, 16, v131
	v_and_b32_e32 v109, 0xffff0000, v131
	v_lshlrev_b32_e32 v112, 16, v133
	v_and_b32_e32 v113, 0xffff0000, v133
	v_lshlrev_b32_e32 v130, 16, v126
	v_and_b32_e32 v126, 0xffff0000, v126
	v_lshlrev_b32_e32 v131, 16, v127
	v_and_b32_e32 v127, 0xffff0000, v127
	v_lshlrev_b32_e32 v133, 16, v129
	v_and_b32_e32 v129, 0xffff0000, v129
	v_fmac_f32_e32 v107, v103, v126
	v_fmac_f32_e32 v108, v98, v131
	v_fmac_f32_e32 v112, v99, v133
	v_fmac_f32_e32 v109, v100, v127
	v_lshl_add_u64 v[98:99], v[166:167], 1, s[14:15]
	v_fmac_f32_e32 v106, v102, v130
	v_fmac_f32_e32 v113, v101, v129
	v_lshl_add_u64 v[104:105], v[158:159], 1, v[98:99]
	v_mul_f32_e32 v98, v142, v142
	v_mul_f32_e32 v99, v143, v143
	v_mul_f32_e32 v101, v107, v107
	v_mul_f32_e32 v102, v109, v109
	v_fmac_f32_e32 v98, v175, v175
	v_fmac_f32_e32 v99, v176, v176
	v_fmac_f32_e32 v101, v106, v106
	v_fmac_f32_e32 v102, v108, v108
	v_add_f32_e32 v98, v98, v99
	v_mul_f32_e32 v99, v144, v144
	v_mul_f32_e32 v100, v145, v145
	v_add_f32_e32 v101, v101, v102
	v_mul_f32_e32 v102, v111, v111
	v_mul_f32_e32 v103, v113, v113
	v_fmac_f32_e32 v99, v177, v177
	v_fmac_f32_e32 v100, v178, v178
	v_fmac_f32_e32 v102, v110, v110
	v_fmac_f32_e32 v103, v112, v112
	v_add_f32_e32 v99, v99, v100
	v_add_f32_e32 v102, v102, v103
	v_add_f32_e32 v100, v98, v99
	v_add_f32_e32 v101, v101, v102
	v_add_f32_e32 v102, v100, v101
	s_nop 1
	v_mov_b32_e32 v103, v102
	s_nop 1
	v_permlane16_swap_b32_e32 v102, v103
	v_cvt_pk_bf16_f32 v98, v175, v142
	v_cvt_pk_bf16_f32 v99, v176, v143
	v_cvt_pk_bf16_f32 v100, v177, v144
	v_cvt_pk_bf16_f32 v101, v178, v145
	global_store_dwordx4 v[104:105], v[98:101], off
	s_waitcnt lgkmcnt(0)
	s_nop 0
	v_add_f32_e32 v98, v102, v103
	s_nop 1
	v_mov_b32_e32 v99, v98
	s_nop 1
	v_permlane32_swap_b32_e32 v98, v99
	v_cvt_pk_bf16_f32 v100, v106, v107
	v_cvt_pk_bf16_f32 v101, v108, v109
	v_cvt_pk_bf16_f32 v102, v110, v111
	v_cvt_pk_bf16_f32 v103, v112, v113
	global_store_dwordx4 v[104:105], v[100:103], off offset:256
	s_and_saveexec_b64 s[36:37], vcc
	s_cbranch_execz .LBB0_229
; __device__ __forceinline__ unsigned cvt_pk_bf16(float lo, float hi) { unsigned r; asm volatile("v_cvt_pk_bf16_f32 %0, %1, %2" : "=v"(r) : "v"(lo), "v"(hi)); return r; }
; __device__ __forceinline__ void publish_row_p(const f32x4 (&xn)[2][2], bf16_t* xbrow, float* ssrow, int fq, int lane) {
;     ...
;     for (int bj = 0; bj < 2; ++bj) { const f32x4 v0 = xn[bj][0], v1 = xn[bj][1];
;         q += ((v0[0] * v0[0] + v0[1] * v0[1]) + (v0[2] * v0[2] + v0[3] * v0[3])) + ((v1[0] * v1[0] + v1[1] * v1[1]) + (v1[2] * v1[2] + v1[3] * v1[3]));
;         u32x4 w; w.x = cvt_pk_bf16(v0[0], v0[1]); w.y = cvt_pk_bf16(v0[2], v0[3]); w.z = cvt_pk_bf16(v1[0], v1[1]); w.w = cvt_pk_bf16(v1[2], v1[3]); *(u32x4*)(xbrow + bj * HALF) = w; }
;     q += __int_as_float(__builtin_amdgcn_ds_bpermute((lane ^ 16) << 2, __float_as_int(q)));
;     q += __int_as_float(__builtin_amdgcn_ds_bpermute((lane ^ 32) << 2, __float_as_int(q)));
;     if (fq == 0) *ssrow = q;
;     __device__ __forceinline__ void operator()(const f32x4 (&acc)[2][2][4][2], const Unit& u, int wr, int wc, int fr, int fq) const {
;     ...
;         for (int r = 0; r < 8; ++r) { const int ai = r >> 2, m = r & 3; const int row = row0 + ai * HALF + m * 16; const size_t off = (size_t)row * ldc + col0; const float rsc = tab[wr * 64 + fr + ai * HALF + m * 16];
; #pragma unroll
;             for (int bj = 0; bj < 2; ++bj) { xv[bj] = xnext[bj]; tv[bj] = tnext[bj]; }
;             if (r < 7) { const int rown = row0 + ((r + 1) >> 2) * HALF + ((r + 1) & 3) * 16;
; #pragma unroll
;                 for (int bj = 0; bj < 2; ++bj) { const size_t o_ = (size_t)rown * ldc + col0 + bj * HALF; xnext[bj] = *(const u32x4*)(Sin + o_); tnext[bj] = *(const u32x4*)(T + o_); } }
;             f32x4 xn[2][2];
; #pragma unroll
;             for (int bj = 0; bj < 2; ++bj) { f32x4 xa, xb, ta, tb; unpack8(xv[bj], xa, xb); unpack8(tv[bj], ta, tb);
;                 const f32x4 a0 = acc[ai][bj][m][0] * rsc, a1 = acc[ai][bj][m][1] * rsc;
; #pragma unroll
;                 for (int e_ = 0; e_ < 4; ++e_) { xn[bj][0][e_] = xa[e_] + __builtin_amdgcn_rcpf(1.0f + __expf(-a0[e_])) * ta[e_]; xn[bj][1][e_] = xb[e_] + __builtin_amdgcn_rcpf(1.0f + __expf(-a1[e_])) * tb[e_]; } }
;             publish_row_p(xn, Sout + off, ss + (size_t)row * 32 + u.pn * 4 + wc, fq, lane); }
	s_waitcnt lgkmcnt(0)
	v_add_f32_e32 v100, v98, v99
	v_lshlrev_b64 v[98:99], 7, v[162:163]
	v_lshl_add_u64 v[98:99], s[16:17], 0, v[98:99]
	v_lshl_add_u64 v[98:99], s[34:35], 2, v[98:99]
	s_lshl_b32 s52, s84, 2
	v_lshl_add_u64 v[98:99], v[98:99], 0, s[52:53]
	global_store_dword v[98:99], v100, off
.LBB0_229:
	s_or_b64 exec, exec, s[36:37]
	v_or_b32_e32 v126, 48, v160
	v_ashrrev_i32_e32 v127, 31, v126
	v_lshlrev_b64 v[128:129], 11, v[126:127]
	s_waitcnt lgkmcnt(0)
	v_lshl_add_u64 v[98:99], v[128:129], 0, v[158:159]
	v_lshlrev_b64 v[98:99], 1, v[98:99]
	v_lshl_add_u64 v[100:101], s[10:11], 0, v[98:99]
	v_lshl_add_u64 v[98:99], s[8:9], 0, v[98:99]
	ds_read_b32 v130, v174 offset:128
	global_load_dwordx4 v[110:113], v[100:101], off
	global_load_dwordx4 v[102:105], v[100:101], off offset:256
	global_load_dwordx4 v[106:109], v[98:99], off
	s_nop 0
	global_load_dwordx4 v[98:101], v[98:99], off offset:256
	s_waitcnt vmcnt(9)
	v_lshlrev_b32_e32 v131, 16, v134
	v_and_b32_e32 v132, 0xffff0000, v134
	v_lshlrev_b32_e32 v133, 16, v135
	s_waitcnt lgkmcnt(0)
	v_mul_f32_e64 v94, v94, -v130
	v_mul_f32_e64 v90, v90, -v130
	v_mul_f32_e64 v95, v95, -v130
	v_mul_f32_e32 v94, 0x3fb8aa3b, v94
	v_mul_f32_e32 v90, 0x3fb8aa3b, v90
	v_mul_f32_e32 v95, 0x3fb8aa3b, v95
	v_mul_f32_e64 v82, v82, -v130
	v_exp_f32_e32 v94, v94
	v_exp_f32_e32 v90, v90
	v_exp_f32_e32 v95, v95
	v_mul_f32_e32 v82, 0x3fb8aa3b, v82
	v_exp_f32_e32 v82, v82
	v_mul_f32_e64 v91, v91, -v130
	v_add_f32_e32 v94, 1.0, v94
	v_add_f32_e32 v90, 1.0, v90
	v_add_f32_e32 v95, 1.0, v95
	v_mul_f32_e32 v91, 0x3fb8aa3b, v91
	v_mul_f32_e64 v83, v83, -v130
	v_rcp_f32_e32 v94, v94
	v_rcp_f32_e32 v90, v90
	v_rcp_f32_e32 v95, v95
	v_exp_f32_e32 v91, v91
	v_add_f32_e32 v82, 1.0, v82
	v_mul_f32_e32 v83, 0x3fb8aa3b, v83
	v_rcp_f32_e32 v82, v82
	v_exp_f32_e32 v83, v83
	v_and_b32_e32 v134, 0xffff0000, v135
	v_lshlrev_b32_e32 v135, 16, v136
	s_waitcnt vmcnt(7)
	v_lshlrev_b32_e32 v139, 16, v122
	v_and_b32_e32 v122, 0xffff0000, v122
	v_lshlrev_b32_e32 v141, 16, v124
	v_fmac_f32_e32 v131, v94, v139
	v_fmac_f32_e32 v135, v90, v141
	v_fmac_f32_e32 v132, v95, v122
	v_add_f32_e32 v90, 1.0, v91
	v_mul_f32_e64 v91, v96, -v130
	v_mul_f32_e64 v92, v92, -v130
	v_lshlrev_b32_e32 v94, 16, v120
	v_and_b32_e32 v95, 0xffff0000, v120
	s_waitcnt vmcnt(6)
	v_lshlrev_b32_e32 v120, 16, v116
	v_mul_f32_e32 v91, 0x3fb8aa3b, v91
	v_mul_f32_e32 v92, 0x3fb8aa3b, v92
	v_fmac_f32_e32 v94, v82, v120
	v_add_f32_e32 v82, 1.0, v83
	v_mul_f32_e64 v83, v88, -v130
	v_mul_f32_e64 v84, v84, -v130
	v_rcp_f32_e32 v90, v90
	v_exp_f32_e32 v91, v91
	v_exp_f32_e32 v92, v92
	v_mul_f32_e32 v83, 0x3fb8aa3b, v83
	v_mul_f32_e32 v84, 0x3fb8aa3b, v84
	v_rcp_f32_e32 v82, v82
	v_exp_f32_e32 v83, v83
	v_exp_f32_e32 v84, v84
	v_and_b32_e32 v136, 0xffff0000, v136
	v_and_b32_e32 v124, 0xffff0000, v124
	v_fmac_f32_e32 v136, v90, v124
	v_add_f32_e32 v90, 1.0, v91
	v_add_f32_e32 v91, 1.0, v92
	v_mul_f32_e64 v92, v97, -v130
	v_mul_f32_e64 v93, v93, -v130
	v_and_b32_e32 v116, 0xffff0000, v116
	v_mul_f32_e32 v92, 0x3fb8aa3b, v92
	v_mul_f32_e32 v93, 0x3fb8aa3b, v93
	v_mul_f32_e64 v87, v87, -v130
	v_fmac_f32_e32 v95, v82, v116
	v_add_f32_e32 v82, 1.0, v83
	v_add_f32_e32 v83, 1.0, v84
	v_mul_f32_e64 v84, v89, -v130
	v_exp_f32_e32 v92, v92
	v_exp_f32_e32 v93, v93
	v_mul_f32_e64 v86, v86, -v130
	v_mul_f32_e32 v87, 0x3fb8aa3b, v87
	v_mul_f32_e32 v84, 0x3fb8aa3b, v84
	v_mul_f32_e64 v85, v85, -v130
	v_mul_f32_e32 v86, 0x3fb8aa3b, v86
	v_exp_f32_e32 v87, v87
	v_exp_f32_e32 v84, v84
	v_mul_f32_e32 v85, 0x3fb8aa3b, v85
	v_exp_f32_e32 v86, v86
	v_exp_f32_e32 v85, v85
	v_add_f32_e32 v92, 1.0, v92
	v_add_f32_e32 v93, 1.0, v93
	v_rcp_f32_e32 v90, v90
	v_rcp_f32_e32 v91, v91
	v_rcp_f32_e32 v92, v92
	v_rcp_f32_e32 v93, v93
	v_add_f32_e32 v87, 1.0, v87
	v_add_f32_e32 v84, 1.0, v84
	v_add_f32_e32 v86, 1.0, v86
	v_rcp_f32_e32 v87, v87
	v_rcp_f32_e32 v82, v82
	v_rcp_f32_e32 v83, v83
	v_rcp_f32_e32 v84, v84
	v_add_f32_e32 v85, 1.0, v85
	v_rcp_f32_e32 v86, v86
	v_rcp_f32_e32 v85, v85
	v_lshlrev_b32_e32 v138, 16, v137
	v_and_b32_e32 v137, 0xffff0000, v137
	v_lshlrev_b32_e32 v140, 16, v123
	v_and_b32_e32 v123, 0xffff0000, v123
	v_lshlrev_b32_e32 v142, 16, v125
	v_and_b32_e32 v125, 0xffff0000, v125
	v_fmac_f32_e32 v133, v90, v140
	v_fmac_f32_e32 v138, v91, v142
	v_fmac_f32_e32 v134, v92, v123
	v_fmac_f32_e32 v137, v93, v125
	v_lshlrev_b32_e32 v90, 16, v118
	v_and_b32_e32 v91, 0xffff0000, v118
	v_lshlrev_b32_e32 v92, 16, v119
	v_and_b32_e32 v93, 0xffff0000, v119
	v_lshlrev_b32_e32 v96, 16, v121
	v_and_b32_e32 v97, 0xffff0000, v121
	v_lshlrev_b32_e32 v118, 16, v114
	v_and_b32_e32 v114, 0xffff0000, v114
	v_lshlrev_b32_e32 v119, 16, v115
	v_and_b32_e32 v115, 0xffff0000, v115
	v_lshlrev_b32_e32 v121, 16, v117
	v_and_b32_e32 v117, 0xffff0000, v117
	v_fmac_f32_e32 v91, v87, v114
	v_fmac_f32_e32 v92, v82, v119
	v_fmac_f32_e32 v96, v83, v121
	v_fmac_f32_e32 v93, v84, v115
	v_lshl_add_u64 v[82:83], v[168:169], 1, s[14:15]
	v_fmac_f32_e32 v90, v86, v118
	v_fmac_f32_e32 v97, v85, v117
	v_lshl_add_u64 v[88:89], v[158:159], 1, v[82:83]
	v_mul_f32_e32 v82, v132, v132
	v_mul_f32_e32 v83, v134, v134
	v_mul_f32_e32 v85, v91, v91
	v_mul_f32_e32 v86, v93, v93
	v_fmac_f32_e32 v82, v131, v131
	v_fmac_f32_e32 v83, v133, v133
	v_fmac_f32_e32 v85, v90, v90
	v_fmac_f32_e32 v86, v92, v92
	v_add_f32_e32 v82, v82, v83
	v_mul_f32_e32 v83, v136, v136
	v_mul_f32_e32 v84, v137, v137
	v_add_f32_e32 v85, v85, v86
	v_mul_f32_e32 v86, v95, v95
	v_mul_f32_e32 v87, v97, v97
	v_fmac_f32_e32 v83, v135, v135
	v_fmac_f32_e32 v84, v138, v138
	v_fmac_f32_e32 v86, v94, v94
	v_fmac_f32_e32 v87, v96, v96
	v_add_f32_e32 v83, v83, v84
	v_add_f32_e32 v86, v86, v87
	v_add_f32_e32 v84, v82, v83
	v_add_f32_e32 v85, v85, v86
	v_add_f32_e32 v86, v84, v85
	s_nop 1
	v_mov_b32_e32 v87, v86
	s_nop 1
	v_permlane16_swap_b32_e32 v86, v87
	v_cvt_pk_bf16_f32 v82, v131, v132
	v_cvt_pk_bf16_f32 v83, v133, v134
	v_cvt_pk_bf16_f32 v84, v135, v136
	v_cvt_pk_bf16_f32 v85, v138, v137
	global_store_dwordx4 v[88:89], v[82:85], off
	s_waitcnt lgkmcnt(0)
	s_nop 0
	v_add_f32_e32 v82, v86, v87
	s_nop 1
	v_mov_b32_e32 v83, v82
	s_nop 1
	v_permlane32_swap_b32_e32 v82, v83
	v_cvt_pk_bf16_f32 v84, v90, v91
	v_cvt_pk_bf16_f32 v85, v92, v93
	v_cvt_pk_bf16_f32 v86, v94, v95
	v_cvt_pk_bf16_f32 v87, v96, v97
	global_store_dwordx4 v[88:89], v[84:87], off offset:256
	s_and_saveexec_b64 s[36:37], vcc
	s_cbranch_execz .LBB0_231
	s_waitcnt lgkmcnt(0)
	v_add_f32_e32 v84, v82, v83
	v_lshlrev_b64 v[82:83], 7, v[164:165]
	v_lshl_add_u64 v[82:83], s[16:17], 0, v[82:83]
	v_lshl_add_u64 v[82:83], s[34:35], 2, v[82:83]
	s_lshl_b32 s52, s84, 2
	v_lshl_add_u64 v[82:83], v[82:83], 0, s[52:53]
	global_store_dword v[82:83], v84, off
; __device__ __forceinline__ unsigned cvt_pk_bf16(float lo, float hi) { unsigned r; asm volatile("v_cvt_pk_bf16_f32 %0, %1, %2" : "=v"(r) : "v"(lo), "v"(hi)); return r; }
; __device__ __forceinline__ void publish_row_p(const f32x4 (&xn)[2][2], bf16_t* xbrow, float* ssrow, int fq, int lane) {
;     ...
;     for (int bj = 0; bj < 2; ++bj) { const f32x4 v0 = xn[bj][0], v1 = xn[bj][1];
;         q += ((v0[0] * v0[0] + v0[1] * v0[1]) + (v0[2] * v0[2] + v0[3] * v0[3])) + ((v1[0] * v1[0] + v1[1] * v1[1]) + (v1[2] * v1[2] + v1[3] * v1[3]));
;         u32x4 w; w.x = cvt_pk_bf16(v0[0], v0[1]); w.y = cvt_pk_bf16(v0[2], v0[3]); w.z = cvt_pk_bf16(v1[0], v1[1]); w.w = cvt_pk_bf16(v1[2], v1[3]); *(u32x4*)(xbrow + bj * HALF) = w; }
;     q += __int_as_float(__builtin_amdgcn_ds_bpermute((lane ^ 16) << 2, __float_as_int(q)));
;     q += __int_as_float(__builtin_amdgcn_ds_bpermute((lane ^ 32) << 2, __float_as_int(q)));
;     if (fq == 0) *ssrow = q;
;     __device__ __forceinline__ void operator()(const f32x4 (&acc)[2][2][4][2], const Unit& u, int wr, int wc, int fr, int fq) const {
;     ...
;         for (int r = 0; r < 8; ++r) { const int ai = r >> 2, m = r & 3; const int row = row0 + ai * HALF + m * 16; const size_t off = (size_t)row * ldc + col0; const float rsc = tab[wr * 64 + fr + ai * HALF + m * 16];
; #pragma unroll
;             for (int bj = 0; bj < 2; ++bj) { xv[bj] = xnext[bj]; tv[bj] = tnext[bj]; }
;             if (r < 7) { const int rown = row0 + ((r + 1) >> 2) * HALF + ((r + 1) & 3) * 16;
; #pragma unroll
;                 for (int bj = 0; bj < 2; ++bj) { const size_t o_ = (size_t)rown * ldc + col0 + bj * HALF; xnext[bj] = *(const u32x4*)(Sin + o_); tnext[bj] = *(const u32x4*)(T + o_); } }
;             f32x4 xn[2][2];
; #pragma unroll
;             for (int bj = 0; bj < 2; ++bj) { f32x4 xa, xb, ta, tb; unpack8(xv[bj], xa, xb); unpack8(tv[bj], ta, tb);
;                 const f32x4 a0 = acc[ai][bj][m][0] * rsc, a1 = acc[ai][bj][m][1] * rsc;
; #pragma unroll
;                 for (int e_ = 0; e_ < 4; ++e_) { xn[bj][0][e_] = xa[e_] + __builtin_amdgcn_rcpf(1.0f + __expf(-a0[e_])) * ta[e_]; xn[bj][1][e_] = xb[e_] + __builtin_amdgcn_rcpf(1.0f + __expf(-a1[e_])) * tb[e_]; } }
;             publish_row_p(xn, Sout + off, ss + (size_t)row * 32 + u.pn * 4 + wc, fq, lane); }
.LBB0_231:
	s_or_b64 exec, exec, s[36:37]
	v_add_u32_e32 v114, 0x80, v160
	v_ashrrev_i32_e32 v115, 31, v114
	v_lshlrev_b64 v[116:117], 11, v[114:115]
	s_waitcnt lgkmcnt(0)
	v_lshl_add_u64 v[82:83], v[116:117], 0, v[158:159]
	v_lshlrev_b64 v[82:83], 1, v[82:83]
	v_lshl_add_u64 v[84:85], s[10:11], 0, v[82:83]
	v_lshl_add_u64 v[82:83], s[8:9], 0, v[82:83]
	ds_read_b32 v118, v174 offset:192
	global_load_dwordx4 v[94:97], v[84:85], off
	global_load_dwordx4 v[86:89], v[84:85], off offset:256
	global_load_dwordx4 v[90:93], v[82:83], off
	s_nop 0
	global_load_dwordx4 v[82:85], v[82:83], off offset:256
	s_waitcnt vmcnt(9)
	v_lshlrev_b32_e32 v119, 16, v110
	v_and_b32_e32 v110, 0xffff0000, v110
	v_lshlrev_b32_e32 v121, 16, v112
	s_waitcnt lgkmcnt(0)
	v_mul_f32_e64 v78, v78, -v118
	v_mul_f32_e64 v74, v74, -v118
	v_mul_f32_e64 v79, v79, -v118
	v_mul_f32_e32 v78, 0x3fb8aa3b, v78
	v_mul_f32_e32 v74, 0x3fb8aa3b, v74
	v_mul_f32_e32 v79, 0x3fb8aa3b, v79
	v_mul_f32_e64 v66, v66, -v118
	v_exp_f32_e32 v78, v78
	v_exp_f32_e32 v74, v74
	v_exp_f32_e32 v79, v79
	v_mul_f32_e32 v66, 0x3fb8aa3b, v66
	v_exp_f32_e32 v66, v66
	v_mul_f32_e64 v75, v75, -v118
	v_add_f32_e32 v78, 1.0, v78
	v_add_f32_e32 v74, 1.0, v74
	v_add_f32_e32 v79, 1.0, v79
	v_mul_f32_e32 v75, 0x3fb8aa3b, v75
	v_mul_f32_e64 v67, v67, -v118
	v_rcp_f32_e32 v78, v78
	v_rcp_f32_e32 v74, v74
	v_rcp_f32_e32 v79, v79
	v_exp_f32_e32 v75, v75
	v_add_f32_e32 v66, 1.0, v66
	v_mul_f32_e32 v67, 0x3fb8aa3b, v67
	v_rcp_f32_e32 v66, v66
	v_exp_f32_e32 v67, v67
	s_waitcnt vmcnt(7)
	v_lshlrev_b32_e32 v123, 16, v106
	v_and_b32_e32 v106, 0xffff0000, v106
	v_lshlrev_b32_e32 v125, 16, v108
	v_fmac_f32_e32 v119, v78, v123
	v_fmac_f32_e32 v121, v74, v125
	v_fmac_f32_e32 v110, v79, v106
	v_add_f32_e32 v74, 1.0, v75
	v_mul_f32_e64 v75, v80, -v118
	v_mul_f32_e64 v76, v76, -v118
	v_lshlrev_b32_e32 v78, 16, v104
	v_and_b32_e32 v79, 0xffff0000, v104
	s_waitcnt vmcnt(6)
	v_lshlrev_b32_e32 v104, 16, v100
	v_mul_f32_e32 v75, 0x3fb8aa3b, v75
	v_mul_f32_e32 v76, 0x3fb8aa3b, v76
	v_fmac_f32_e32 v78, v66, v104
	v_add_f32_e32 v66, 1.0, v67
	v_mul_f32_e64 v67, v72, -v118
	v_mul_f32_e64 v68, v68, -v118
	v_rcp_f32_e32 v74, v74
	v_exp_f32_e32 v75, v75
	v_exp_f32_e32 v76, v76
	v_mul_f32_e32 v67, 0x3fb8aa3b, v67
	v_mul_f32_e32 v68, 0x3fb8aa3b, v68
	v_rcp_f32_e32 v66, v66
	v_exp_f32_e32 v67, v67
	v_exp_f32_e32 v68, v68
	v_and_b32_e32 v112, 0xffff0000, v112
	v_and_b32_e32 v108, 0xffff0000, v108
	v_fmac_f32_e32 v112, v74, v108
	v_add_f32_e32 v74, 1.0, v75
	v_add_f32_e32 v75, 1.0, v76
	v_mul_f32_e64 v76, v81, -v118
	v_mul_f32_e64 v77, v77, -v118
	v_and_b32_e32 v100, 0xffff0000, v100
	v_mul_f32_e32 v76, 0x3fb8aa3b, v76
	v_mul_f32_e32 v77, 0x3fb8aa3b, v77
	v_mul_f32_e64 v71, v71, -v118
	v_fmac_f32_e32 v79, v66, v100
	v_add_f32_e32 v66, 1.0, v67
	v_add_f32_e32 v67, 1.0, v68
	v_mul_f32_e64 v68, v73, -v118
	v_exp_f32_e32 v76, v76
	v_exp_f32_e32 v77, v77
	v_mul_f32_e64 v70, v70, -v118
	v_mul_f32_e32 v71, 0x3fb8aa3b, v71
	v_mul_f32_e32 v68, 0x3fb8aa3b, v68
	v_mul_f32_e64 v69, v69, -v118
	v_mul_f32_e32 v70, 0x3fb8aa3b, v70
	v_exp_f32_e32 v71, v71
	v_exp_f32_e32 v68, v68
	v_mul_f32_e32 v69, 0x3fb8aa3b, v69
	v_exp_f32_e32 v70, v70
	v_exp_f32_e32 v69, v69
	v_add_f32_e32 v76, 1.0, v76
	v_add_f32_e32 v77, 1.0, v77
	v_rcp_f32_e32 v74, v74
	v_rcp_f32_e32 v75, v75
	v_rcp_f32_e32 v76, v76
	v_rcp_f32_e32 v77, v77
	v_add_f32_e32 v71, 1.0, v71
	v_add_f32_e32 v68, 1.0, v68
	v_add_f32_e32 v70, 1.0, v70
	v_rcp_f32_e32 v71, v71
	v_rcp_f32_e32 v66, v66
	v_rcp_f32_e32 v67, v67
	v_rcp_f32_e32 v68, v68
	v_add_f32_e32 v69, 1.0, v69
	v_rcp_f32_e32 v70, v70
	v_rcp_f32_e32 v69, v69
	v_lshlrev_b32_e32 v120, 16, v111
	v_and_b32_e32 v111, 0xffff0000, v111
	v_lshlrev_b32_e32 v122, 16, v113
	v_and_b32_e32 v113, 0xffff0000, v113
	v_lshlrev_b32_e32 v124, 16, v107
	v_and_b32_e32 v107, 0xffff0000, v107
	v_lshlrev_b32_e32 v130, 16, v109
	v_and_b32_e32 v109, 0xffff0000, v109
	v_fmac_f32_e32 v120, v74, v124
	v_fmac_f32_e32 v122, v75, v130
	v_fmac_f32_e32 v111, v76, v107
	v_fmac_f32_e32 v113, v77, v109
	v_lshlrev_b32_e32 v74, 16, v102
	v_and_b32_e32 v75, 0xffff0000, v102
	v_lshlrev_b32_e32 v76, 16, v103
	v_and_b32_e32 v77, 0xffff0000, v103
	v_lshlrev_b32_e32 v80, 16, v105
	v_and_b32_e32 v81, 0xffff0000, v105
	v_lshlrev_b32_e32 v102, 16, v98
	v_and_b32_e32 v98, 0xffff0000, v98
	v_lshlrev_b32_e32 v103, 16, v99
	v_and_b32_e32 v99, 0xffff0000, v99
	v_lshlrev_b32_e32 v105, 16, v101
	v_and_b32_e32 v101, 0xffff0000, v101
	v_fmac_f32_e32 v75, v71, v98
	v_fmac_f32_e32 v76, v66, v103
	v_fmac_f32_e32 v80, v67, v105
	v_fmac_f32_e32 v77, v68, v99
	v_lshl_add_u64 v[66:67], v[128:129], 1, s[14:15]
	v_fmac_f32_e32 v74, v70, v102
	v_fmac_f32_e32 v81, v69, v101
	v_lshl_add_u64 v[72:73], v[158:159], 1, v[66:67]
	v_mul_f32_e32 v66, v110, v110
	v_mul_f32_e32 v67, v111, v111
	v_mul_f32_e32 v69, v75, v75
	v_mul_f32_e32 v70, v77, v77
	v_fmac_f32_e32 v66, v119, v119
	v_fmac_f32_e32 v67, v120, v120
	v_fmac_f32_e32 v69, v74, v74
	v_fmac_f32_e32 v70, v76, v76
	v_add_f32_e32 v66, v66, v67
	v_mul_f32_e32 v67, v112, v112
	v_mul_f32_e32 v68, v113, v113
	v_add_f32_e32 v69, v69, v70
	v_mul_f32_e32 v70, v79, v79
	v_mul_f32_e32 v71, v81, v81
	v_fmac_f32_e32 v67, v121, v121
	v_fmac_f32_e32 v68, v122, v122
	v_fmac_f32_e32 v70, v78, v78
	v_fmac_f32_e32 v71, v80, v80
	v_add_f32_e32 v67, v67, v68
	v_add_f32_e32 v70, v70, v71
	v_add_f32_e32 v68, v66, v67
	v_add_f32_e32 v69, v69, v70
	v_add_f32_e32 v70, v68, v69
	s_nop 1
	v_mov_b32_e32 v71, v70
	s_nop 1
	v_permlane16_swap_b32_e32 v70, v71
	v_cvt_pk_bf16_f32 v66, v119, v110
	v_cvt_pk_bf16_f32 v67, v120, v111
	v_cvt_pk_bf16_f32 v68, v121, v112
	v_cvt_pk_bf16_f32 v69, v122, v113
	global_store_dwordx4 v[72:73], v[66:69], off
	s_waitcnt lgkmcnt(0)
	s_nop 0
	v_add_f32_e32 v66, v70, v71
	s_nop 1
	v_mov_b32_e32 v67, v66
	s_nop 1
	v_permlane32_swap_b32_e32 v66, v67
	v_cvt_pk_bf16_f32 v68, v74, v75
	v_cvt_pk_bf16_f32 v69, v76, v77
	v_cvt_pk_bf16_f32 v70, v78, v79
	v_cvt_pk_bf16_f32 v71, v80, v81
	global_store_dwordx4 v[72:73], v[68:71], off offset:256
	s_and_saveexec_b64 s[36:37], vcc
	s_cbranch_execz .LBB0_233
	s_waitcnt lgkmcnt(0)
	v_add_f32_e32 v68, v66, v67
	v_lshlrev_b64 v[66:67], 7, v[126:127]
	v_lshl_add_u64 v[66:67], s[16:17], 0, v[66:67]
	v_lshl_add_u64 v[66:67], s[34:35], 2, v[66:67]
	s_lshl_b32 s52, s84, 2
	v_lshl_add_u64 v[66:67], v[66:67], 0, s[52:53]
	global_store_dword v[66:67], v68, off
; __device__ __forceinline__ unsigned cvt_pk_bf16(float lo, float hi) { unsigned r; asm volatile("v_cvt_pk_bf16_f32 %0, %1, %2" : "=v"(r) : "v"(lo), "v"(hi)); return r; }
; __device__ __forceinline__ void publish_row_p(const f32x4 (&xn)[2][2], bf16_t* xbrow, float* ssrow, int fq, int lane) {
;     ...
;     for (int bj = 0; bj < 2; ++bj) { const f32x4 v0 = xn[bj][0], v1 = xn[bj][1];
;         q += ((v0[0] * v0[0] + v0[1] * v0[1]) + (v0[2] * v0[2] + v0[3] * v0[3])) + ((v1[0] * v1[0] + v1[1] * v1[1]) + (v1[2] * v1[2] + v1[3] * v1[3]));
;         u32x4 w; w.x = cvt_pk_bf16(v0[0], v0[1]); w.y = cvt_pk_bf16(v0[2], v0[3]); w.z = cvt_pk_bf16(v1[0], v1[1]); w.w = cvt_pk_bf16(v1[2], v1[3]); *(u32x4*)(xbrow + bj * HALF) = w; }
;     q += __int_as_float(__builtin_amdgcn_ds_bpermute((lane ^ 16) << 2, __float_as_int(q)));
;     q += __int_as_float(__builtin_amdgcn_ds_bpermute((lane ^ 32) << 2, __float_as_int(q)));
;     if (fq == 0) *ssrow = q;
;     __device__ __forceinline__ void operator()(const f32x4 (&acc)[2][2][4][2], const Unit& u, int wr, int wc, int fr, int fq) const {
;     ...
;         for (int r = 0; r < 8; ++r) { const int ai = r >> 2, m = r & 3; const int row = row0 + ai * HALF + m * 16; const size_t off = (size_t)row * ldc + col0; const float rsc = tab[wr * 64 + fr + ai * HALF + m * 16];
; #pragma unroll
;             for (int bj = 0; bj < 2; ++bj) { xv[bj] = xnext[bj]; tv[bj] = tnext[bj]; }
;             if (r < 7) { const int rown = row0 + ((r + 1) >> 2) * HALF + ((r + 1) & 3) * 16;
; #pragma unroll
;                 for (int bj = 0; bj < 2; ++bj) { const size_t o_ = (size_t)rown * ldc + col0 + bj * HALF; xnext[bj] = *(const u32x4*)(Sin + o_); tnext[bj] = *(const u32x4*)(T + o_); } }
;             f32x4 xn[2][2];
; #pragma unroll
;             for (int bj = 0; bj < 2; ++bj) { f32x4 xa, xb, ta, tb; unpack8(xv[bj], xa, xb); unpack8(tv[bj], ta, tb);
;                 const f32x4 a0 = acc[ai][bj][m][0] * rsc, a1 = acc[ai][bj][m][1] * rsc;
; #pragma unroll
;                 for (int e_ = 0; e_ < 4; ++e_) { xn[bj][0][e_] = xa[e_] + __builtin_amdgcn_rcpf(1.0f + __expf(-a0[e_])) * ta[e_]; xn[bj][1][e_] = xb[e_] + __builtin_amdgcn_rcpf(1.0f + __expf(-a1[e_])) * tb[e_]; } }
;             publish_row_p(xn, Sout + off, ss + (size_t)row * 32 + u.pn * 4 + wc, fq, lane); }
.LBB0_233:
	s_or_b64 exec, exec, s[36:37]
	v_or_b32_e32 v98, 16, v114
	v_ashrrev_i32_e32 v99, 31, v98
	v_lshlrev_b64 v[100:101], 11, v[98:99]
	s_waitcnt lgkmcnt(0)
	v_lshl_add_u64 v[66:67], v[100:101], 0, v[158:159]
	v_lshlrev_b64 v[66:67], 1, v[66:67]
	v_lshl_add_u64 v[68:69], s[10:11], 0, v[66:67]
	v_lshl_add_u64 v[66:67], s[8:9], 0, v[66:67]
	ds_read_b32 v102, v174 offset:512
	global_load_dwordx4 v[78:81], v[68:69], off
	global_load_dwordx4 v[70:73], v[68:69], off offset:256
	global_load_dwordx4 v[74:77], v[66:67], off
	s_nop 0
	global_load_dwordx4 v[66:69], v[66:67], off offset:256
	s_waitcnt vmcnt(9)
	v_lshlrev_b32_e32 v103, 16, v94
	v_and_b32_e32 v94, 0xffff0000, v94
	v_lshlrev_b32_e32 v105, 16, v96
	s_waitcnt lgkmcnt(0)
	v_mul_f32_e64 v62, v62, -v102
	v_mul_f32_e64 v58, v58, -v102
	v_mul_f32_e64 v63, v63, -v102
	v_mul_f32_e32 v62, 0x3fb8aa3b, v62
	v_mul_f32_e32 v58, 0x3fb8aa3b, v58
	v_mul_f32_e32 v63, 0x3fb8aa3b, v63
	v_mul_f32_e64 v50, v50, -v102
	v_exp_f32_e32 v62, v62
	v_exp_f32_e32 v58, v58
	v_exp_f32_e32 v63, v63
	v_mul_f32_e32 v50, 0x3fb8aa3b, v50
	v_exp_f32_e32 v50, v50
	v_mul_f32_e64 v59, v59, -v102
	v_add_f32_e32 v62, 1.0, v62
	v_add_f32_e32 v58, 1.0, v58
	v_add_f32_e32 v63, 1.0, v63
	v_mul_f32_e32 v59, 0x3fb8aa3b, v59
	v_mul_f32_e64 v51, v51, -v102
	v_rcp_f32_e32 v62, v62
	v_rcp_f32_e32 v58, v58
	v_rcp_f32_e32 v63, v63
	v_exp_f32_e32 v59, v59
	v_add_f32_e32 v50, 1.0, v50
	v_mul_f32_e32 v51, 0x3fb8aa3b, v51
	v_rcp_f32_e32 v50, v50
	v_exp_f32_e32 v51, v51
	s_waitcnt vmcnt(7)
	v_lshlrev_b32_e32 v107, 16, v90
	v_and_b32_e32 v90, 0xffff0000, v90
	v_lshlrev_b32_e32 v109, 16, v92
	v_fmac_f32_e32 v103, v62, v107
	v_fmac_f32_e32 v105, v58, v109
	v_fmac_f32_e32 v94, v63, v90
	v_add_f32_e32 v58, 1.0, v59
	v_mul_f32_e64 v59, v64, -v102
	v_mul_f32_e64 v60, v60, -v102
	v_lshlrev_b32_e32 v62, 16, v88
	v_and_b32_e32 v63, 0xffff0000, v88
	s_waitcnt vmcnt(6)
	v_lshlrev_b32_e32 v88, 16, v84
	v_mul_f32_e32 v59, 0x3fb8aa3b, v59
	v_mul_f32_e32 v60, 0x3fb8aa3b, v60
	v_fmac_f32_e32 v62, v50, v88
	v_add_f32_e32 v50, 1.0, v51
	v_mul_f32_e64 v51, v56, -v102
	v_mul_f32_e64 v52, v52, -v102
	v_rcp_f32_e32 v58, v58
	v_exp_f32_e32 v59, v59
	v_exp_f32_e32 v60, v60
	v_mul_f32_e32 v51, 0x3fb8aa3b, v51
	v_mul_f32_e32 v52, 0x3fb8aa3b, v52
	v_rcp_f32_e32 v50, v50
	v_exp_f32_e32 v51, v51
	v_exp_f32_e32 v52, v52
	v_and_b32_e32 v96, 0xffff0000, v96
	v_and_b32_e32 v92, 0xffff0000, v92
	v_fmac_f32_e32 v96, v58, v92
	v_add_f32_e32 v58, 1.0, v59
	v_add_f32_e32 v59, 1.0, v60
	v_mul_f32_e64 v60, v65, -v102
	v_mul_f32_e64 v61, v61, -v102
	v_and_b32_e32 v84, 0xffff0000, v84
	v_mul_f32_e32 v60, 0x3fb8aa3b, v60
	v_mul_f32_e32 v61, 0x3fb8aa3b, v61
	v_mul_f32_e64 v55, v55, -v102
	v_fmac_f32_e32 v63, v50, v84
	v_add_f32_e32 v50, 1.0, v51
	v_add_f32_e32 v51, 1.0, v52
	v_mul_f32_e64 v52, v57, -v102
	v_exp_f32_e32 v60, v60
	v_exp_f32_e32 v61, v61
	v_mul_f32_e64 v54, v54, -v102
	v_mul_f32_e32 v55, 0x3fb8aa3b, v55
	v_mul_f32_e32 v52, 0x3fb8aa3b, v52
	v_mul_f32_e64 v53, v53, -v102
	v_mul_f32_e32 v54, 0x3fb8aa3b, v54
	v_exp_f32_e32 v55, v55
	v_exp_f32_e32 v52, v52
	v_mul_f32_e32 v53, 0x3fb8aa3b, v53
	v_exp_f32_e32 v54, v54
	v_exp_f32_e32 v53, v53
	v_add_f32_e32 v60, 1.0, v60
	v_add_f32_e32 v61, 1.0, v61
	v_rcp_f32_e32 v58, v58
	v_rcp_f32_e32 v59, v59
	v_rcp_f32_e32 v60, v60
	v_rcp_f32_e32 v61, v61
	v_add_f32_e32 v55, 1.0, v55
	v_add_f32_e32 v52, 1.0, v52
	v_add_f32_e32 v54, 1.0, v54
	v_rcp_f32_e32 v55, v55
	v_rcp_f32_e32 v50, v50
	v_rcp_f32_e32 v51, v51
	v_rcp_f32_e32 v52, v52
	v_add_f32_e32 v53, 1.0, v53
	v_rcp_f32_e32 v54, v54
	v_rcp_f32_e32 v53, v53
	v_lshlrev_b32_e32 v104, 16, v95
	v_and_b32_e32 v95, 0xffff0000, v95
	v_lshlrev_b32_e32 v106, 16, v97
	v_and_b32_e32 v97, 0xffff0000, v97
	v_lshlrev_b32_e32 v108, 16, v91
	v_and_b32_e32 v91, 0xffff0000, v91
	v_lshlrev_b32_e32 v110, 16, v93
	v_and_b32_e32 v93, 0xffff0000, v93
	v_fmac_f32_e32 v104, v58, v108
	v_fmac_f32_e32 v106, v59, v110
	v_fmac_f32_e32 v95, v60, v91
	v_fmac_f32_e32 v97, v61, v93
	v_lshlrev_b32_e32 v58, 16, v86
	v_and_b32_e32 v59, 0xffff0000, v86
	v_lshlrev_b32_e32 v60, 16, v87
	v_and_b32_e32 v61, 0xffff0000, v87
	v_lshlrev_b32_e32 v64, 16, v89
	v_and_b32_e32 v65, 0xffff0000, v89
	v_lshlrev_b32_e32 v86, 16, v82
	v_and_b32_e32 v82, 0xffff0000, v82
	v_lshlrev_b32_e32 v87, 16, v83
	v_and_b32_e32 v83, 0xffff0000, v83
	v_lshlrev_b32_e32 v89, 16, v85
	v_and_b32_e32 v85, 0xffff0000, v85
	v_fmac_f32_e32 v59, v55, v82
	v_fmac_f32_e32 v60, v50, v87
	v_fmac_f32_e32 v64, v51, v89
	v_fmac_f32_e32 v61, v52, v83
	v_lshl_add_u64 v[50:51], v[116:117], 1, s[14:15]
	v_fmac_f32_e32 v58, v54, v86
	v_fmac_f32_e32 v65, v53, v85
	v_lshl_add_u64 v[56:57], v[158:159], 1, v[50:51]
	v_mul_f32_e32 v50, v94, v94
	v_mul_f32_e32 v51, v95, v95
	v_mul_f32_e32 v53, v59, v59
	v_mul_f32_e32 v54, v61, v61
	v_fmac_f32_e32 v50, v103, v103
	v_fmac_f32_e32 v51, v104, v104
	v_fmac_f32_e32 v53, v58, v58
	v_fmac_f32_e32 v54, v60, v60
	v_add_f32_e32 v50, v50, v51
	v_mul_f32_e32 v51, v96, v96
	v_mul_f32_e32 v52, v97, v97
	v_add_f32_e32 v53, v53, v54
	v_mul_f32_e32 v54, v63, v63
	v_mul_f32_e32 v55, v65, v65
	v_fmac_f32_e32 v51, v105, v105
	v_fmac_f32_e32 v52, v106, v106
	v_fmac_f32_e32 v54, v62, v62
	v_fmac_f32_e32 v55, v64, v64
	v_add_f32_e32 v51, v51, v52
	v_add_f32_e32 v54, v54, v55
	v_add_f32_e32 v52, v50, v51
	v_add_f32_e32 v53, v53, v54
	v_add_f32_e32 v54, v52, v53
	s_nop 1
	v_mov_b32_e32 v55, v54
	s_nop 1
	v_permlane16_swap_b32_e32 v54, v55
	v_cvt_pk_bf16_f32 v50, v103, v94
	v_cvt_pk_bf16_f32 v51, v104, v95
	v_cvt_pk_bf16_f32 v52, v105, v96
	v_cvt_pk_bf16_f32 v53, v106, v97
	global_store_dwordx4 v[56:57], v[50:53], off
	s_waitcnt lgkmcnt(0)
	s_nop 0
	v_add_f32_e32 v50, v54, v55
	s_nop 1
	v_mov_b32_e32 v51, v50
	s_nop 1
	v_permlane32_swap_b32_e32 v50, v51
	v_cvt_pk_bf16_f32 v52, v58, v59
	v_cvt_pk_bf16_f32 v53, v60, v61
	v_cvt_pk_bf16_f32 v54, v62, v63
	v_cvt_pk_bf16_f32 v55, v64, v65
	global_store_dwordx4 v[56:57], v[52:55], off offset:256
	s_and_saveexec_b64 s[36:37], vcc
	s_cbranch_execz .LBB0_235
	s_waitcnt lgkmcnt(0)
	v_add_f32_e32 v52, v50, v51
	v_lshlrev_b64 v[50:51], 7, v[114:115]
	v_lshl_add_u64 v[50:51], s[16:17], 0, v[50:51]
	v_lshl_add_u64 v[50:51], s[34:35], 2, v[50:51]
	s_lshl_b32 s52, s84, 2
	v_lshl_add_u64 v[50:51], v[50:51], 0, s[52:53]
	global_store_dword v[50:51], v52, off
; __device__ __forceinline__ unsigned cvt_pk_bf16(float lo, float hi) { unsigned r; asm volatile("v_cvt_pk_bf16_f32 %0, %1, %2" : "=v"(r) : "v"(lo), "v"(hi)); return r; }
; __device__ __forceinline__ void publish_row_p(const f32x4 (&xn)[2][2], bf16_t* xbrow, float* ssrow, int fq, int lane) {
;     ...
;     for (int bj = 0; bj < 2; ++bj) { const f32x4 v0 = xn[bj][0], v1 = xn[bj][1];
;         q += ((v0[0] * v0[0] + v0[1] * v0[1]) + (v0[2] * v0[2] + v0[3] * v0[3])) + ((v1[0] * v1[0] + v1[1] * v1[1]) + (v1[2] * v1[2] + v1[3] * v1[3]));
;         u32x4 w; w.x = cvt_pk_bf16(v0[0], v0[1]); w.y = cvt_pk_bf16(v0[2], v0[3]); w.z = cvt_pk_bf16(v1[0], v1[1]); w.w = cvt_pk_bf16(v1[2], v1[3]); *(u32x4*)(xbrow + bj * HALF) = w; }
;     q += __int_as_float(__builtin_amdgcn_ds_bpermute((lane ^ 16) << 2, __float_as_int(q)));
;     q += __int_as_float(__builtin_amdgcn_ds_bpermute((lane ^ 32) << 2, __float_as_int(q)));
;     if (fq == 0) *ssrow = q;
;     __device__ __forceinline__ void operator()(const f32x4 (&acc)[2][2][4][2], const Unit& u, int wr, int wc, int fr, int fq) const {
;     ...
;         for (int r = 0; r < 8; ++r) { const int ai = r >> 2, m = r & 3; const int row = row0 + ai * HALF + m * 16; const size_t off = (size_t)row * ldc + col0; const float rsc = tab[wr * 64 + fr + ai * HALF + m * 16];
; #pragma unroll
;             for (int bj = 0; bj < 2; ++bj) { xv[bj] = xnext[bj]; tv[bj] = tnext[bj]; }
;             if (r < 7) { const int rown = row0 + ((r + 1) >> 2) * HALF + ((r + 1) & 3) * 16;
; #pragma unroll
;                 for (int bj = 0; bj < 2; ++bj) { const size_t o_ = (size_t)rown * ldc + col0 + bj * HALF; xnext[bj] = *(const u32x4*)(Sin + o_); tnext[bj] = *(const u32x4*)(T + o_); } }
;             f32x4 xn[2][2];
; #pragma unroll
;             for (int bj = 0; bj < 2; ++bj) { f32x4 xa, xb, ta, tb; unpack8(xv[bj], xa, xb); unpack8(tv[bj], ta, tb);
;                 const f32x4 a0 = acc[ai][bj][m][0] * rsc, a1 = acc[ai][bj][m][1] * rsc;
; #pragma unroll
;                 for (int e_ = 0; e_ < 4; ++e_) { xn[bj][0][e_] = xa[e_] + __builtin_amdgcn_rcpf(1.0f + __expf(-a0[e_])) * ta[e_]; xn[bj][1][e_] = xb[e_] + __builtin_amdgcn_rcpf(1.0f + __expf(-a1[e_])) * tb[e_]; } }
;             publish_row_p(xn, Sout + off, ss + (size_t)row * 32 + u.pn * 4 + wc, fq, lane); }
.LBB0_235:
	s_or_b64 exec, exec, s[36:37]
	v_or_b32_e32 v82, 32, v114
	v_ashrrev_i32_e32 v83, 31, v82
	v_lshlrev_b64 v[84:85], 11, v[82:83]
	s_waitcnt lgkmcnt(0)
	v_lshl_add_u64 v[50:51], v[84:85], 0, v[158:159]
	v_lshlrev_b64 v[50:51], 1, v[50:51]
	v_lshl_add_u64 v[52:53], s[10:11], 0, v[50:51]
	v_lshl_add_u64 v[50:51], s[8:9], 0, v[50:51]
	ds_read_b32 v86, v174 offset:576
	global_load_dwordx4 v[62:65], v[52:53], off
	global_load_dwordx4 v[54:57], v[52:53], off offset:256
	global_load_dwordx4 v[58:61], v[50:51], off
	s_nop 0
	global_load_dwordx4 v[50:53], v[50:51], off offset:256
	s_waitcnt vmcnt(9)
	v_lshlrev_b32_e32 v87, 16, v78
	v_and_b32_e32 v78, 0xffff0000, v78
	v_lshlrev_b32_e32 v89, 16, v80
	s_waitcnt lgkmcnt(0)
	v_mul_f32_e64 v46, v46, -v86
	v_mul_f32_e64 v42, v42, -v86
	v_mul_f32_e64 v47, v47, -v86
	v_mul_f32_e32 v46, 0x3fb8aa3b, v46
	v_mul_f32_e32 v42, 0x3fb8aa3b, v42
	v_mul_f32_e32 v47, 0x3fb8aa3b, v47
	v_mul_f32_e64 v34, v34, -v86
	v_exp_f32_e32 v46, v46
	v_exp_f32_e32 v42, v42
	v_exp_f32_e32 v47, v47
	v_mul_f32_e32 v34, 0x3fb8aa3b, v34
	v_exp_f32_e32 v34, v34
	v_mul_f32_e64 v43, v43, -v86
	v_add_f32_e32 v46, 1.0, v46
	v_add_f32_e32 v42, 1.0, v42
	v_add_f32_e32 v47, 1.0, v47
	v_mul_f32_e32 v43, 0x3fb8aa3b, v43
	v_mul_f32_e64 v35, v35, -v86
	v_rcp_f32_e32 v46, v46
	v_rcp_f32_e32 v42, v42
	v_rcp_f32_e32 v47, v47
	v_exp_f32_e32 v43, v43
	v_add_f32_e32 v34, 1.0, v34
	v_mul_f32_e32 v35, 0x3fb8aa3b, v35
	v_rcp_f32_e32 v34, v34
	v_exp_f32_e32 v35, v35
	s_waitcnt vmcnt(7)
	v_lshlrev_b32_e32 v91, 16, v74
	v_and_b32_e32 v74, 0xffff0000, v74
	v_lshlrev_b32_e32 v93, 16, v76
	v_fmac_f32_e32 v87, v46, v91
	v_fmac_f32_e32 v89, v42, v93
	v_fmac_f32_e32 v78, v47, v74
	v_add_f32_e32 v42, 1.0, v43
	v_mul_f32_e64 v43, v48, -v86
	v_mul_f32_e64 v44, v44, -v86
	v_lshlrev_b32_e32 v46, 16, v72
	v_and_b32_e32 v47, 0xffff0000, v72
	s_waitcnt vmcnt(6)
	v_lshlrev_b32_e32 v72, 16, v68
	v_mul_f32_e32 v43, 0x3fb8aa3b, v43
	v_mul_f32_e32 v44, 0x3fb8aa3b, v44
	v_fmac_f32_e32 v46, v34, v72
	v_add_f32_e32 v34, 1.0, v35
	v_mul_f32_e64 v35, v40, -v86
	v_mul_f32_e64 v36, v36, -v86
	v_rcp_f32_e32 v42, v42
	v_exp_f32_e32 v43, v43
	v_exp_f32_e32 v44, v44
	v_mul_f32_e32 v35, 0x3fb8aa3b, v35
	v_mul_f32_e32 v36, 0x3fb8aa3b, v36
	v_rcp_f32_e32 v34, v34
	v_exp_f32_e32 v35, v35
	v_exp_f32_e32 v36, v36
	v_and_b32_e32 v80, 0xffff0000, v80
	v_and_b32_e32 v76, 0xffff0000, v76
	v_fmac_f32_e32 v80, v42, v76
	v_add_f32_e32 v42, 1.0, v43
	v_add_f32_e32 v43, 1.0, v44
	v_mul_f32_e64 v44, v49, -v86
	v_mul_f32_e64 v45, v45, -v86
	v_and_b32_e32 v68, 0xffff0000, v68
	v_mul_f32_e32 v44, 0x3fb8aa3b, v44
	v_mul_f32_e32 v45, 0x3fb8aa3b, v45
	v_mul_f32_e64 v39, v39, -v86
	v_fmac_f32_e32 v47, v34, v68
	v_add_f32_e32 v34, 1.0, v35
	v_add_f32_e32 v35, 1.0, v36
	v_mul_f32_e64 v36, v41, -v86
	v_exp_f32_e32 v44, v44
	v_exp_f32_e32 v45, v45
	v_mul_f32_e64 v38, v38, -v86
	v_mul_f32_e32 v39, 0x3fb8aa3b, v39
	v_mul_f32_e32 v36, 0x3fb8aa3b, v36
	v_mul_f32_e64 v37, v37, -v86
	v_mul_f32_e32 v38, 0x3fb8aa3b, v38
	v_exp_f32_e32 v39, v39
	v_exp_f32_e32 v36, v36
	v_mul_f32_e32 v37, 0x3fb8aa3b, v37
	v_exp_f32_e32 v38, v38
	v_exp_f32_e32 v37, v37
	v_add_f32_e32 v44, 1.0, v44
	v_add_f32_e32 v45, 1.0, v45
	v_rcp_f32_e32 v42, v42
	v_rcp_f32_e32 v43, v43
	v_rcp_f32_e32 v44, v44
	v_rcp_f32_e32 v45, v45
	v_add_f32_e32 v39, 1.0, v39
	v_add_f32_e32 v36, 1.0, v36
	v_add_f32_e32 v38, 1.0, v38
	v_rcp_f32_e32 v39, v39
	v_rcp_f32_e32 v34, v34
	v_rcp_f32_e32 v35, v35
	v_rcp_f32_e32 v36, v36
	v_add_f32_e32 v37, 1.0, v37
	v_rcp_f32_e32 v38, v38
	v_rcp_f32_e32 v37, v37
	v_lshlrev_b32_e32 v88, 16, v79
	v_and_b32_e32 v79, 0xffff0000, v79
	v_lshlrev_b32_e32 v90, 16, v81
	v_and_b32_e32 v81, 0xffff0000, v81
	v_lshlrev_b32_e32 v92, 16, v75
	v_and_b32_e32 v75, 0xffff0000, v75
	v_lshlrev_b32_e32 v94, 16, v77
	v_and_b32_e32 v77, 0xffff0000, v77
	v_fmac_f32_e32 v88, v42, v92
	v_fmac_f32_e32 v90, v43, v94
	v_fmac_f32_e32 v79, v44, v75
	v_fmac_f32_e32 v81, v45, v77
	v_lshlrev_b32_e32 v42, 16, v70
	v_and_b32_e32 v43, 0xffff0000, v70
	v_lshlrev_b32_e32 v44, 16, v71
	v_and_b32_e32 v45, 0xffff0000, v71
	v_lshlrev_b32_e32 v48, 16, v73
	v_and_b32_e32 v49, 0xffff0000, v73
	v_lshlrev_b32_e32 v70, 16, v66
	v_and_b32_e32 v66, 0xffff0000, v66
	v_lshlrev_b32_e32 v71, 16, v67
	v_and_b32_e32 v67, 0xffff0000, v67
	v_lshlrev_b32_e32 v73, 16, v69
	v_and_b32_e32 v69, 0xffff0000, v69
	v_fmac_f32_e32 v43, v39, v66
	v_fmac_f32_e32 v44, v34, v71
	v_fmac_f32_e32 v48, v35, v73
	v_fmac_f32_e32 v45, v36, v67
	v_lshl_add_u64 v[34:35], v[100:101], 1, s[14:15]
	v_fmac_f32_e32 v42, v38, v70
	v_fmac_f32_e32 v49, v37, v69
	v_lshl_add_u64 v[40:41], v[158:159], 1, v[34:35]
	v_mul_f32_e32 v34, v78, v78
	v_mul_f32_e32 v35, v79, v79
	v_mul_f32_e32 v37, v43, v43
	v_mul_f32_e32 v38, v45, v45
	v_fmac_f32_e32 v34, v87, v87
	v_fmac_f32_e32 v35, v88, v88
	v_fmac_f32_e32 v37, v42, v42
	v_fmac_f32_e32 v38, v44, v44
	v_add_f32_e32 v34, v34, v35
	v_mul_f32_e32 v35, v80, v80
	v_mul_f32_e32 v36, v81, v81
	v_add_f32_e32 v37, v37, v38
	v_mul_f32_e32 v38, v47, v47
	v_mul_f32_e32 v39, v49, v49
	v_fmac_f32_e32 v35, v89, v89
	v_fmac_f32_e32 v36, v90, v90
	v_fmac_f32_e32 v38, v46, v46
	v_fmac_f32_e32 v39, v48, v48
	v_add_f32_e32 v35, v35, v36
	v_add_f32_e32 v38, v38, v39
	v_add_f32_e32 v36, v34, v35
	v_add_f32_e32 v37, v37, v38
	v_add_f32_e32 v38, v36, v37
	s_nop 1
	v_mov_b32_e32 v39, v38
	s_nop 1
	v_permlane16_swap_b32_e32 v38, v39
	v_cvt_pk_bf16_f32 v34, v87, v78
	v_cvt_pk_bf16_f32 v35, v88, v79
	v_cvt_pk_bf16_f32 v36, v89, v80
	v_cvt_pk_bf16_f32 v37, v90, v81
	global_store_dwordx4 v[40:41], v[34:37], off
	s_waitcnt lgkmcnt(0)
	s_nop 0
	v_add_f32_e32 v34, v38, v39
	s_nop 1
	v_mov_b32_e32 v35, v34
	s_nop 1
	v_permlane32_swap_b32_e32 v34, v35
	v_cvt_pk_bf16_f32 v36, v42, v43
	v_cvt_pk_bf16_f32 v37, v44, v45
	v_cvt_pk_bf16_f32 v38, v46, v47
	v_cvt_pk_bf16_f32 v39, v48, v49
	global_store_dwordx4 v[40:41], v[36:39], off offset:256
	s_and_saveexec_b64 s[36:37], vcc
	s_cbranch_execz .LBB0_237
	s_waitcnt lgkmcnt(0)
	v_add_f32_e32 v36, v34, v35
	v_lshlrev_b64 v[34:35], 7, v[98:99]
	v_lshl_add_u64 v[34:35], s[16:17], 0, v[34:35]
	v_lshl_add_u64 v[34:35], s[34:35], 2, v[34:35]
	s_lshl_b32 s52, s84, 2
	v_lshl_add_u64 v[34:35], v[34:35], 0, s[52:53]
	global_store_dword v[34:35], v36, off
; __device__ __forceinline__ unsigned cvt_pk_bf16(float lo, float hi) { unsigned r; asm volatile("v_cvt_pk_bf16_f32 %0, %1, %2" : "=v"(r) : "v"(lo), "v"(hi)); return r; }
; __device__ __forceinline__ void publish_row_p(const f32x4 (&xn)[2][2], bf16_t* xbrow, float* ssrow, int fq, int lane) {
;     ...
;     for (int bj = 0; bj < 2; ++bj) { const f32x4 v0 = xn[bj][0], v1 = xn[bj][1];
;         q += ((v0[0] * v0[0] + v0[1] * v0[1]) + (v0[2] * v0[2] + v0[3] * v0[3])) + ((v1[0] * v1[0] + v1[1] * v1[1]) + (v1[2] * v1[2] + v1[3] * v1[3]));
;         u32x4 w; w.x = cvt_pk_bf16(v0[0], v0[1]); w.y = cvt_pk_bf16(v0[2], v0[3]); w.z = cvt_pk_bf16(v1[0], v1[1]); w.w = cvt_pk_bf16(v1[2], v1[3]); *(u32x4*)(xbrow + bj * HALF) = w; }
;     q += __int_as_float(__builtin_amdgcn_ds_bpermute((lane ^ 16) << 2, __float_as_int(q)));
;     q += __int_as_float(__builtin_amdgcn_ds_bpermute((lane ^ 32) << 2, __float_as_int(q)));
;     if (fq == 0) *ssrow = q;
;     __device__ __forceinline__ void operator()(const f32x4 (&acc)[2][2][4][2], const Unit& u, int wr, int wc, int fr, int fq) const {
;     ...
;         for (int r = 0; r < 8; ++r) { const int ai = r >> 2, m = r & 3; const int row = row0 + ai * HALF + m * 16; const size_t off = (size_t)row * ldc + col0; const float rsc = tab[wr * 64 + fr + ai * HALF + m * 16];
; #pragma unroll
;             for (int bj = 0; bj < 2; ++bj) { xv[bj] = xnext[bj]; tv[bj] = tnext[bj]; }
;             if (r < 7) { const int rown = row0 + ((r + 1) >> 2) * HALF + ((r + 1) & 3) * 16;
; #pragma unroll
;                 for (int bj = 0; bj < 2; ++bj) { const size_t o_ = (size_t)rown * ldc + col0 + bj * HALF; xnext[bj] = *(const u32x4*)(Sin + o_); tnext[bj] = *(const u32x4*)(T + o_); } }
;             f32x4 xn[2][2];
; #pragma unroll
;             for (int bj = 0; bj < 2; ++bj) { f32x4 xa, xb, ta, tb; unpack8(xv[bj], xa, xb); unpack8(tv[bj], ta, tb);
;                 const f32x4 a0 = acc[ai][bj][m][0] * rsc, a1 = acc[ai][bj][m][1] * rsc;
; #pragma unroll
;                 for (int e_ = 0; e_ < 4; ++e_) { xn[bj][0][e_] = xa[e_] + __builtin_amdgcn_rcpf(1.0f + __expf(-a0[e_])) * ta[e_]; xn[bj][1][e_] = xb[e_] + __builtin_amdgcn_rcpf(1.0f + __expf(-a1[e_])) * tb[e_]; } }
;             publish_row_p(xn, Sout + off, ss + (size_t)row * 32 + u.pn * 4 + wc, fq, lane); }
.LBB0_237:
	s_or_b64 exec, exec, s[36:37]
	v_or_b32_e32 v66, 48, v114
	v_ashrrev_i32_e32 v67, 31, v66
	v_lshlrev_b64 v[68:69], 11, v[66:67]
	s_waitcnt lgkmcnt(0)
	v_lshl_add_u64 v[34:35], v[68:69], 0, v[158:159]
	v_lshlrev_b64 v[34:35], 1, v[34:35]
	v_lshl_add_u64 v[36:37], s[10:11], 0, v[34:35]
	v_lshl_add_u64 v[34:35], s[8:9], 0, v[34:35]
	ds_read_b32 v70, v174 offset:640
	global_load_dwordx4 v[46:49], v[36:37], off
	global_load_dwordx4 v[38:41], v[36:37], off offset:256
	global_load_dwordx4 v[42:45], v[34:35], off
	s_nop 0
	global_load_dwordx4 v[34:37], v[34:35], off offset:256
	s_waitcnt vmcnt(9)
	v_lshlrev_b32_e32 v71, 16, v62
	v_and_b32_e32 v62, 0xffff0000, v62
	v_lshlrev_b32_e32 v73, 16, v64
	s_waitcnt lgkmcnt(0)
	v_mul_f32_e64 v30, v30, -v70
	v_mul_f32_e64 v26, v26, -v70
	v_mul_f32_e64 v31, v31, -v70
	v_mul_f32_e32 v30, 0x3fb8aa3b, v30
	v_mul_f32_e32 v26, 0x3fb8aa3b, v26
	v_mul_f32_e32 v31, 0x3fb8aa3b, v31
	v_mul_f32_e64 v18, v18, -v70
	v_exp_f32_e32 v30, v30
	v_exp_f32_e32 v26, v26
	v_exp_f32_e32 v31, v31
	v_mul_f32_e32 v18, 0x3fb8aa3b, v18
	v_exp_f32_e32 v18, v18
	v_mul_f32_e64 v27, v27, -v70
	v_add_f32_e32 v30, 1.0, v30
	v_add_f32_e32 v26, 1.0, v26
	v_add_f32_e32 v31, 1.0, v31
	v_mul_f32_e32 v27, 0x3fb8aa3b, v27
	v_mul_f32_e64 v19, v19, -v70
	v_rcp_f32_e32 v30, v30
	v_rcp_f32_e32 v26, v26
	v_rcp_f32_e32 v31, v31
	v_exp_f32_e32 v27, v27
	v_add_f32_e32 v18, 1.0, v18
	v_mul_f32_e32 v19, 0x3fb8aa3b, v19
	v_rcp_f32_e32 v18, v18
	v_exp_f32_e32 v19, v19
	s_waitcnt vmcnt(7)
	v_lshlrev_b32_e32 v75, 16, v58
	v_and_b32_e32 v58, 0xffff0000, v58
	v_lshlrev_b32_e32 v77, 16, v60
	v_fmac_f32_e32 v71, v30, v75
	v_fmac_f32_e32 v73, v26, v77
	v_fmac_f32_e32 v62, v31, v58
	v_add_f32_e32 v26, 1.0, v27
	v_mul_f32_e64 v27, v32, -v70
	v_mul_f32_e64 v28, v28, -v70
	v_lshlrev_b32_e32 v30, 16, v56
	v_and_b32_e32 v31, 0xffff0000, v56
	s_waitcnt vmcnt(6)
	v_lshlrev_b32_e32 v56, 16, v52
	v_mul_f32_e32 v27, 0x3fb8aa3b, v27
	v_mul_f32_e32 v28, 0x3fb8aa3b, v28
	v_fmac_f32_e32 v30, v18, v56
	v_add_f32_e32 v18, 1.0, v19
	v_mul_f32_e64 v19, v24, -v70
	v_mul_f32_e64 v20, v20, -v70
	v_rcp_f32_e32 v26, v26
	v_exp_f32_e32 v27, v27
	v_exp_f32_e32 v28, v28
	v_mul_f32_e32 v19, 0x3fb8aa3b, v19
	v_mul_f32_e32 v20, 0x3fb8aa3b, v20
	v_rcp_f32_e32 v18, v18
	v_exp_f32_e32 v19, v19
	v_exp_f32_e32 v20, v20
	v_and_b32_e32 v64, 0xffff0000, v64
	v_and_b32_e32 v60, 0xffff0000, v60
	v_fmac_f32_e32 v64, v26, v60
	v_add_f32_e32 v26, 1.0, v27
	v_add_f32_e32 v27, 1.0, v28
	v_mul_f32_e64 v28, v33, -v70
	v_mul_f32_e64 v29, v29, -v70
	v_and_b32_e32 v52, 0xffff0000, v52
	v_mul_f32_e32 v28, 0x3fb8aa3b, v28
	v_mul_f32_e32 v29, 0x3fb8aa3b, v29
	v_mul_f32_e64 v23, v23, -v70
	v_fmac_f32_e32 v31, v18, v52
	v_add_f32_e32 v18, 1.0, v19
	v_add_f32_e32 v19, 1.0, v20
	v_mul_f32_e64 v20, v25, -v70
	v_exp_f32_e32 v28, v28
	v_exp_f32_e32 v29, v29
	v_mul_f32_e64 v22, v22, -v70
	v_mul_f32_e32 v23, 0x3fb8aa3b, v23
	v_mul_f32_e32 v20, 0x3fb8aa3b, v20
	v_mul_f32_e64 v21, v21, -v70
	v_mul_f32_e32 v22, 0x3fb8aa3b, v22
	v_exp_f32_e32 v23, v23
	v_exp_f32_e32 v20, v20
	v_mul_f32_e32 v21, 0x3fb8aa3b, v21
	v_exp_f32_e32 v22, v22
	v_exp_f32_e32 v21, v21
	v_add_f32_e32 v28, 1.0, v28
	v_add_f32_e32 v29, 1.0, v29
	v_rcp_f32_e32 v26, v26
	v_rcp_f32_e32 v27, v27
	v_rcp_f32_e32 v28, v28
	v_rcp_f32_e32 v29, v29
	v_add_f32_e32 v23, 1.0, v23
	v_add_f32_e32 v20, 1.0, v20
	v_add_f32_e32 v22, 1.0, v22
	v_rcp_f32_e32 v23, v23
	v_rcp_f32_e32 v18, v18
	v_rcp_f32_e32 v19, v19
	v_rcp_f32_e32 v20, v20
	v_add_f32_e32 v21, 1.0, v21
	v_rcp_f32_e32 v22, v22
	v_rcp_f32_e32 v21, v21
	v_lshlrev_b32_e32 v72, 16, v63
	v_and_b32_e32 v63, 0xffff0000, v63
	v_lshlrev_b32_e32 v74, 16, v65
	v_and_b32_e32 v65, 0xffff0000, v65
	v_lshlrev_b32_e32 v76, 16, v59
	v_and_b32_e32 v59, 0xffff0000, v59
	v_lshlrev_b32_e32 v78, 16, v61
	v_and_b32_e32 v61, 0xffff0000, v61
	v_fmac_f32_e32 v72, v26, v76
	v_fmac_f32_e32 v74, v27, v78
	v_fmac_f32_e32 v63, v28, v59
	v_fmac_f32_e32 v65, v29, v61
	v_lshlrev_b32_e32 v26, 16, v54
	v_and_b32_e32 v27, 0xffff0000, v54
	v_lshlrev_b32_e32 v28, 16, v55
	v_and_b32_e32 v29, 0xffff0000, v55
	v_lshlrev_b32_e32 v32, 16, v57
	v_and_b32_e32 v33, 0xffff0000, v57
	v_lshlrev_b32_e32 v54, 16, v50
	v_and_b32_e32 v50, 0xffff0000, v50
	v_lshlrev_b32_e32 v55, 16, v51
	v_and_b32_e32 v51, 0xffff0000, v51
	v_lshlrev_b32_e32 v57, 16, v53
	v_and_b32_e32 v53, 0xffff0000, v53
	v_fmac_f32_e32 v27, v23, v50
	v_fmac_f32_e32 v28, v18, v55
	v_fmac_f32_e32 v32, v19, v57
	v_fmac_f32_e32 v29, v20, v51
	v_lshl_add_u64 v[18:19], v[84:85], 1, s[14:15]
	v_fmac_f32_e32 v26, v22, v54
	v_fmac_f32_e32 v33, v21, v53
	v_lshl_add_u64 v[24:25], v[158:159], 1, v[18:19]
	v_mul_f32_e32 v18, v62, v62
	v_mul_f32_e32 v19, v63, v63
	v_mul_f32_e32 v21, v27, v27
	v_mul_f32_e32 v22, v29, v29
	v_fmac_f32_e32 v18, v71, v71
	v_fmac_f32_e32 v19, v72, v72
	v_fmac_f32_e32 v21, v26, v26
	v_fmac_f32_e32 v22, v28, v28
	v_add_f32_e32 v18, v18, v19
	v_mul_f32_e32 v19, v64, v64
	v_mul_f32_e32 v20, v65, v65
	v_add_f32_e32 v21, v21, v22
	v_mul_f32_e32 v22, v31, v31
	v_mul_f32_e32 v23, v33, v33
	v_fmac_f32_e32 v19, v73, v73
	v_fmac_f32_e32 v20, v74, v74
	v_fmac_f32_e32 v22, v30, v30
	v_fmac_f32_e32 v23, v32, v32
	v_add_f32_e32 v19, v19, v20
	v_add_f32_e32 v22, v22, v23
	v_add_f32_e32 v20, v18, v19
	v_add_f32_e32 v21, v21, v22
	v_add_f32_e32 v22, v20, v21
	s_nop 1
	v_mov_b32_e32 v23, v22
	s_nop 1
	v_permlane16_swap_b32_e32 v22, v23
	v_cvt_pk_bf16_f32 v18, v71, v62
	v_cvt_pk_bf16_f32 v19, v72, v63
	v_cvt_pk_bf16_f32 v20, v73, v64
	v_cvt_pk_bf16_f32 v21, v74, v65
	global_store_dwordx4 v[24:25], v[18:21], off
	s_waitcnt lgkmcnt(0)
	s_nop 0
	v_add_f32_e32 v18, v22, v23
	s_nop 1
	v_mov_b32_e32 v19, v18
	s_nop 1
	v_permlane32_swap_b32_e32 v18, v19
	v_cvt_pk_bf16_f32 v20, v26, v27
	v_cvt_pk_bf16_f32 v21, v28, v29
	v_cvt_pk_bf16_f32 v22, v30, v31
	v_cvt_pk_bf16_f32 v23, v32, v33
	global_store_dwordx4 v[24:25], v[20:23], off offset:256
	s_and_saveexec_b64 s[36:37], vcc
	s_cbranch_execz .LBB0_239
	s_waitcnt lgkmcnt(0)
	v_add_f32_e32 v20, v18, v19
	v_lshlrev_b64 v[18:19], 7, v[82:83]
	v_lshl_add_u64 v[18:19], s[16:17], 0, v[18:19]
	v_lshl_add_u64 v[18:19], s[34:35], 2, v[18:19]
	s_lshl_b32 s52, s84, 2
	v_lshl_add_u64 v[18:19], v[18:19], 0, s[52:53]
	global_store_dword v[18:19], v20, off
; __device__ __forceinline__ unsigned cvt_pk_bf16(float lo, float hi) { unsigned r; asm volatile("v_cvt_pk_bf16_f32 %0, %1, %2" : "=v"(r) : "v"(lo), "v"(hi)); return r; }
; __device__ __forceinline__ void publish_row_p(const f32x4 (&xn)[2][2], bf16_t* xbrow, float* ssrow, int fq, int lane) {
;     ...
;     for (int bj = 0; bj < 2; ++bj) { const f32x4 v0 = xn[bj][0], v1 = xn[bj][1];
;         q += ((v0[0] * v0[0] + v0[1] * v0[1]) + (v0[2] * v0[2] + v0[3] * v0[3])) + ((v1[0] * v1[0] + v1[1] * v1[1]) + (v1[2] * v1[2] + v1[3] * v1[3]));
;         u32x4 w; w.x = cvt_pk_bf16(v0[0], v0[1]); w.y = cvt_pk_bf16(v0[2], v0[3]); w.z = cvt_pk_bf16(v1[0], v1[1]); w.w = cvt_pk_bf16(v1[2], v1[3]); *(u32x4*)(xbrow + bj * HALF) = w; }
;     q += __int_as_float(__builtin_amdgcn_ds_bpermute((lane ^ 16) << 2, __float_as_int(q)));
;     q += __int_as_float(__builtin_amdgcn_ds_bpermute((lane ^ 32) << 2, __float_as_int(q)));
;     if (fq == 0) *ssrow = q;
;     __device__ __forceinline__ void operator()(const f32x4 (&acc)[2][2][4][2], const Unit& u, int wr, int wc, int fr, int fq) const {
;     ...
;         for (int r = 0; r < 8; ++r) { const int ai = r >> 2, m = r & 3; const int row = row0 + ai * HALF + m * 16; const size_t off = (size_t)row * ldc + col0; const float rsc = tab[wr * 64 + fr + ai * HALF + m * 16];
; #pragma unroll
;             for (int bj = 0; bj < 2; ++bj) { xv[bj] = xnext[bj]; tv[bj] = tnext[bj]; }
;             if (r < 7) { const int rown = row0 + ((r + 1) >> 2) * HALF + ((r + 1) & 3) * 16;
; #pragma unroll
;                 for (int bj = 0; bj < 2; ++bj) { const size_t o_ = (size_t)rown * ldc + col0 + bj * HALF; xnext[bj] = *(const u32x4*)(Sin + o_); tnext[bj] = *(const u32x4*)(T + o_); } }
;             f32x4 xn[2][2];
; #pragma unroll
;             for (int bj = 0; bj < 2; ++bj) { f32x4 xa, xb, ta, tb; unpack8(xv[bj], xa, xb); unpack8(tv[bj], ta, tb);
;                 const f32x4 a0 = acc[ai][bj][m][0] * rsc, a1 = acc[ai][bj][m][1] * rsc;
; #pragma unroll
;                 for (int e_ = 0; e_ < 4; ++e_) { xn[bj][0][e_] = xa[e_] + __builtin_amdgcn_rcpf(1.0f + __expf(-a0[e_])) * ta[e_]; xn[bj][1][e_] = xb[e_] + __builtin_amdgcn_rcpf(1.0f + __expf(-a1[e_])) * tb[e_]; } }
;             publish_row_p(xn, Sout + off, ss + (size_t)row * 32 + u.pn * 4 + wc, fq, lane); }
.LBB0_239:
	s_or_b64 exec, exec, s[36:37]
	ds_read_b32 v18, v174 offset:704
	s_waitcnt vmcnt(5) lgkmcnt(1)
	v_lshlrev_b32_e32 v19, 16, v46
	v_lshlrev_b32_e32 v23, 16, v48
	s_waitcnt vmcnt(3)
	v_lshlrev_b32_e32 v27, 16, v42
	v_lshlrev_b32_e32 v31, 16, v44
	s_waitcnt lgkmcnt(0)
	v_mul_f32_e64 v14, v14, -v18
	v_mul_f32_e64 v10, v10, -v18
	v_mul_f32_e32 v14, 0x3fb8aa3b, v14
	v_mul_f32_e32 v10, 0x3fb8aa3b, v10
	v_mul_f32_e64 v2, v2, -v18
	v_exp_f32_e32 v14, v14
	v_exp_f32_e32 v10, v10
	v_mul_f32_e32 v2, 0x3fb8aa3b, v2
	v_exp_f32_e32 v2, v2
	v_mul_f32_e64 v11, v11, -v18
	v_add_f32_e32 v14, 1.0, v14
	v_mul_f32_e64 v15, v15, -v18
	v_add_f32_e32 v10, 1.0, v10
	v_mul_f32_e32 v11, 0x3fb8aa3b, v11
	v_mul_f32_e64 v3, v3, -v18
	v_mul_f32_e32 v15, 0x3fb8aa3b, v15
	v_rcp_f32_e32 v14, v14
	v_rcp_f32_e32 v10, v10
	v_exp_f32_e32 v11, v11
	v_add_f32_e32 v2, 1.0, v2
	v_mul_f32_e32 v3, 0x3fb8aa3b, v3
	v_exp_f32_e32 v15, v15
	v_rcp_f32_e32 v2, v2
	v_exp_f32_e32 v3, v3
	v_fmac_f32_e32 v19, v14, v27
	v_fmac_f32_e32 v23, v10, v31
	v_add_f32_e32 v10, 1.0, v11
	v_mul_f32_e64 v11, v16, -v18
	v_mul_f32_e64 v12, v12, -v18
	v_lshlrev_b32_e32 v14, 16, v40
	s_waitcnt vmcnt(2)
	v_lshlrev_b32_e32 v31, 16, v36
	v_add_f32_e32 v15, 1.0, v15
	v_mul_f32_e32 v11, 0x3fb8aa3b, v11
	v_mul_f32_e32 v12, 0x3fb8aa3b, v12
	v_fmac_f32_e32 v14, v2, v31
	v_add_f32_e32 v2, 1.0, v3
	v_mul_f32_e64 v3, v8, -v18
	v_mul_f32_e64 v4, v4, -v18
	v_rcp_f32_e32 v15, v15
	v_rcp_f32_e32 v10, v10
	v_exp_f32_e32 v11, v11
	v_exp_f32_e32 v12, v12
	v_mul_f32_e32 v3, 0x3fb8aa3b, v3
	v_mul_f32_e32 v4, 0x3fb8aa3b, v4
	v_rcp_f32_e32 v2, v2
	v_exp_f32_e32 v3, v3
	v_exp_f32_e32 v4, v4
	v_and_b32_e32 v20, 0xffff0000, v46
	v_and_b32_e32 v24, 0xffff0000, v48
	v_and_b32_e32 v28, 0xffff0000, v42
	v_and_b32_e32 v32, 0xffff0000, v44
	v_fmac_f32_e32 v20, v15, v28
	v_fmac_f32_e32 v24, v10, v32
	v_add_f32_e32 v10, 1.0, v11
	v_add_f32_e32 v11, 1.0, v12
	v_mul_f32_e64 v12, v17, -v18
	v_mul_f32_e64 v13, v13, -v18
	v_and_b32_e32 v15, 0xffff0000, v40
	v_and_b32_e32 v32, 0xffff0000, v36
	v_mul_f32_e32 v12, 0x3fb8aa3b, v12
	v_mul_f32_e32 v13, 0x3fb8aa3b, v13
	v_mul_f32_e64 v7, v7, -v18
	v_fmac_f32_e32 v15, v2, v32
	v_add_f32_e32 v2, 1.0, v3
	v_add_f32_e32 v3, 1.0, v4
	v_mul_f32_e64 v4, v9, -v18
	v_exp_f32_e32 v12, v12
	v_exp_f32_e32 v13, v13
	v_mul_f32_e64 v6, v6, -v18
	v_mul_f32_e32 v7, 0x3fb8aa3b, v7
	v_mul_f32_e32 v4, 0x3fb8aa3b, v4
	v_mul_f32_e64 v5, v5, -v18
	v_mul_f32_e32 v6, 0x3fb8aa3b, v6
	v_exp_f32_e32 v7, v7
	v_exp_f32_e32 v4, v4
	v_mul_f32_e32 v5, 0x3fb8aa3b, v5
	v_exp_f32_e32 v6, v6
	v_exp_f32_e32 v5, v5
	v_add_f32_e32 v12, 1.0, v12
	v_add_f32_e32 v13, 1.0, v13
	v_rcp_f32_e32 v10, v10
	v_rcp_f32_e32 v11, v11
	v_rcp_f32_e32 v12, v12
	v_rcp_f32_e32 v13, v13
	v_add_f32_e32 v7, 1.0, v7
	v_add_f32_e32 v4, 1.0, v4
	v_add_f32_e32 v6, 1.0, v6
	v_rcp_f32_e32 v7, v7
	v_rcp_f32_e32 v2, v2
	v_rcp_f32_e32 v3, v3
	v_rcp_f32_e32 v4, v4
	v_add_f32_e32 v5, 1.0, v5
	v_rcp_f32_e32 v6, v6
	v_rcp_f32_e32 v5, v5
	v_lshlrev_b32_e32 v21, 16, v47
	v_and_b32_e32 v22, 0xffff0000, v47
	v_lshlrev_b32_e32 v25, 16, v49
	v_and_b32_e32 v26, 0xffff0000, v49
	v_lshlrev_b32_e32 v29, 16, v43
	v_and_b32_e32 v30, 0xffff0000, v43
	v_lshlrev_b32_e32 v33, 16, v45
	v_and_b32_e32 v42, 0xffff0000, v45
	v_fmac_f32_e32 v21, v10, v29
	v_fmac_f32_e32 v25, v11, v33
	v_fmac_f32_e32 v22, v12, v30
	v_fmac_f32_e32 v26, v13, v42
	v_and_b32_e32 v11, 0xffff0000, v38
	v_lshlrev_b32_e32 v12, 16, v39
	v_and_b32_e32 v13, 0xffff0000, v39
	v_lshlrev_b32_e32 v16, 16, v41
	v_and_b32_e32 v28, 0xffff0000, v34
	v_lshlrev_b32_e32 v29, 16, v35
	v_and_b32_e32 v30, 0xffff0000, v35
	v_lshlrev_b32_e32 v33, 16, v37
	v_lshlrev_b32_e32 v10, 16, v38
	v_and_b32_e32 v17, 0xffff0000, v41
	v_lshlrev_b32_e32 v27, 16, v34
	v_and_b32_e32 v34, 0xffff0000, v37
	v_fmac_f32_e32 v11, v7, v28
	v_fmac_f32_e32 v12, v2, v29
	v_fmac_f32_e32 v16, v3, v33
	v_fmac_f32_e32 v13, v4, v30
	v_lshl_add_u64 v[2:3], v[68:69], 1, s[14:15]
	v_fmac_f32_e32 v10, v6, v27
	v_fmac_f32_e32 v17, v5, v34
	v_lshl_add_u64 v[8:9], v[158:159], 1, v[2:3]
	v_mul_f32_e32 v2, v20, v20
	v_mul_f32_e32 v3, v22, v22
	v_mul_f32_e32 v5, v11, v11
	v_mul_f32_e32 v6, v13, v13
	v_fmac_f32_e32 v2, v19, v19
	v_fmac_f32_e32 v3, v21, v21
	v_fmac_f32_e32 v5, v10, v10
	v_fmac_f32_e32 v6, v12, v12
	v_add_f32_e32 v2, v2, v3
	v_mul_f32_e32 v3, v24, v24
	v_mul_f32_e32 v4, v26, v26
	v_add_f32_e32 v5, v5, v6
	v_mul_f32_e32 v6, v15, v15
	v_mul_f32_e32 v7, v17, v17
	v_fmac_f32_e32 v3, v23, v23
	v_fmac_f32_e32 v4, v25, v25
	v_fmac_f32_e32 v6, v14, v14
	v_fmac_f32_e32 v7, v16, v16
	v_add_f32_e32 v3, v3, v4
	v_add_f32_e32 v6, v6, v7
	v_add_f32_e32 v4, v2, v3
	v_add_f32_e32 v5, v5, v6
	v_add_f32_e32 v6, v4, v5
	s_nop 1
	v_mov_b32_e32 v7, v6
	s_nop 1
	v_permlane16_swap_b32_e32 v6, v7
	v_cvt_pk_bf16_f32 v2, v19, v20
	v_cvt_pk_bf16_f32 v3, v21, v22
	v_cvt_pk_bf16_f32 v4, v23, v24
	v_cvt_pk_bf16_f32 v5, v25, v26
	global_store_dwordx4 v[8:9], v[2:5], off
	s_waitcnt lgkmcnt(0)
	s_nop 0
	v_add_f32_e32 v2, v6, v7
	s_nop 1
	v_mov_b32_e32 v0, v2
	s_nop 1
	v_permlane32_swap_b32_e32 v2, v0
	v_cvt_pk_bf16_f32 v4, v10, v11
	v_cvt_pk_bf16_f32 v5, v12, v13
	v_cvt_pk_bf16_f32 v6, v14, v15
	v_cvt_pk_bf16_f32 v7, v16, v17
	global_store_dwordx4 v[8:9], v[4:7], off offset:256
	s_and_saveexec_b64 s[36:37], vcc
	s_cbranch_execz .LBB0_241
	s_waitcnt lgkmcnt(0)
	v_add_f32_e32 v0, v2, v0
	v_lshlrev_b64 v[2:3], 7, v[66:67]
	v_lshl_add_u64 v[2:3], s[16:17], 0, v[2:3]
	v_lshl_add_u64 v[2:3], s[34:35], 2, v[2:3]
	s_lshl_b32 s52, s84, 2
	v_lshl_add_u64 v[2:3], v[2:3], 0, s[52:53]
	global_store_dword v[2:3], v0, off

; __device__ __forceinline__ unsigned cvt_pk_bf16(float lo, float hi) { unsigned r; asm volatile("v_cvt_pk_bf16_f32 %0, %1, %2" : "=v"(r) : "v"(lo), "v"(hi)); return r; }
; __device__ __forceinline__ void publish_row_p(const f32x4 (&xn)[2][2], bf16_t* xbrow, float* ssrow, int fq, int lane) {
;     ...
;     for (int bj = 0; bj < 2; ++bj) { const f32x4 v0 = xn[bj][0], v1 = xn[bj][1];
;         q += ((v0[0] * v0[0] + v0[1] * v0[1]) + (v0[2] * v0[2] + v0[3] * v0[3])) + ((v1[0] * v1[0] + v1[1] * v1[1]) + (v1[2] * v1[2] + v1[3] * v1[3]));
;         u32x4 w; w.x = cvt_pk_bf16(v0[0], v0[1]); w.y = cvt_pk_bf16(v0[2], v0[3]); w.z = cvt_pk_bf16(v1[0], v1[1]); w.w = cvt_pk_bf16(v1[2], v1[3]); *(u32x4*)(xbrow + bj * HALF) = w; }
;     q += __int_as_float(__builtin_amdgcn_ds_bpermute((lane ^ 16) << 2, __float_as_int(q)));
;     q += __int_as_float(__builtin_amdgcn_ds_bpermute((lane ^ 32) << 2, __float_as_int(q)));
;     if (fq == 0) *ssrow = q;
;     __device__ __forceinline__ void operator()(const f32x4 (&acc)[2][2][4][2], const Unit& u, int wr, int wc, int fr, int fq) const {
;     ...
;         for (int bj = 0; bj < 2; ++bj) xnext[bj] = *(const u32x4*)(S + (size_t)row0 * ldc + col0 + bj * HALF);
; #pragma unroll
;         for (int r = 0; r < 8; ++r) { const int ai = r >> 2, m = r & 3; const int row = row0 + ai * HALF + m * 16;
; #pragma unroll
;             for (int bj = 0; bj < 2; ++bj) xv[bj] = xnext[bj];
;             if (r < 7) { const int rown = row0 + ((r + 1) >> 2) * HALF + ((r + 1) & 3) * 16;
; #pragma unroll
;                 for (int bj = 0; bj < 2; ++bj) xnext[bj] = *(const u32x4*)(S + (size_t)rown * ldc + col0 + bj * HALF); }
;             f32x4 xn[2][2];
; #pragma unroll
;             for (int bj = 0; bj < 2; ++bj) { f32x4 a, b; unpack8(xv[bj], a, b); xn[bj][0] = a + acc[ai][bj][m][0] * alpha; xn[bj][1] = b + acc[ai][bj][m][1] * alpha; }
;             publish_row_p(xn, S + (size_t)row * ldc + col0, ss + (size_t)row * 32 + u.pn * 4 + wc, fq, lane); }
.LBB0_604:
	s_mov_b32 s34, -1
	s_nop 0
	v_mbcnt_lo_u32_b32 v130, s34, 0
	v_mbcnt_hi_u32_b32 v134, s34, v130
	s_lshl_b32 s34, s46, 8
	v_and_b32_e32 v135, 15, v134
	s_add_i32 s34, s34, s84
	v_or_b32_e32 v150, s34, v135
	s_lshl_b32 s34, s3, 8
	v_lshrrev_b32_e32 v136, 4, v134
	s_or_b32 s34, s34, s85
	v_lshl_add_u32 v148, v136, 3, s34
	v_ashrrev_i32_e32 v151, 31, v150
	v_lshlrev_b64 v[130:131], 12, v[150:151]
	v_ashrrev_i32_e32 v149, 31, v148
	v_lshl_add_u64 v[130:131], s[22:23], 0, v[130:131]
	v_lshlrev_b64 v[132:133], 1, v[148:149]
	v_lshl_add_u64 v[156:157], v[130:131], 0, v[132:133]
	global_load_dwordx4 v[164:167], v[156:157], off
	global_load_dwordx4 v[168:171], v[156:157], off offset:256
	v_or_b32_e32 v152, 16, v150
	v_lshlrev_b32_e32 v130, 6, v136
	v_lshlrev_b32_e32 v131, 2, v135
	s_movk_i32 s34, 0x80
	v_ashrrev_i32_e32 v153, 31, v152
	v_bitop3_b32 v162, v130, 64, v131 bitop3:0x36
	v_bitop3_b32 v161, v130, s34, v131 bitop3:0x36
	v_lshlrev_b64 v[130:131], 12, v[152:153]
	v_lshl_add_u64 v[130:131], s[22:23], 0, v[130:131]
	v_lshl_add_u64 v[154:155], v[130:131], 0, v[132:133]
	v_cmp_gt_u32_e32 vcc, 16, v134
	global_load_dwordx4 v[134:137], v[154:155], off
	global_load_dwordx4 v[130:133], v[154:155], off offset:256
	s_lshl_b32 s34, s3, 2
	s_ashr_i32 s35, s34, 31
	s_waitcnt vmcnt(0)
	v_lshlrev_b32_e32 v172, 16, v164
	v_and_b32_e32 v173, 0xffff0000, v164
	v_lshlrev_b32_e32 v164, 16, v165
	v_and_b32_e32 v165, 0xffff0000, v165
	v_lshlrev_b32_e32 v174, 16, v166
	v_and_b32_e32 v175, 0xffff0000, v166
	v_lshlrev_b32_e32 v166, 16, v167
	v_and_b32_e32 v167, 0xffff0000, v167
	v_pk_fma_f32 v[128:129], s[26:27], v[128:129], v[164:165]
	v_pk_fma_f32 v[126:127], s[14:15], v[126:127], v[172:173]
	v_pk_fma_f32 v[124:125], s[26:27], v[124:125], v[166:167]
	v_lshlrev_b32_e32 v164, 16, v168
	v_and_b32_e32 v165, 0xffff0000, v168
	v_lshlrev_b32_e32 v166, 16, v169
	v_and_b32_e32 v167, 0xffff0000, v169
	v_lshlrev_b32_e32 v168, 16, v170
	v_and_b32_e32 v169, 0xffff0000, v170
	v_pk_fma_f32 v[120:121], s[26:27], v[120:121], v[166:167]
	v_pk_fma_f32 v[166:167], s[14:15], v[114:115], v[168:169]
	v_mul_f32_e32 v114, v127, v127
	v_mul_f32_e32 v115, v129, v129
	v_pk_fma_f32 v[122:123], s[14:15], v[122:123], v[174:175]
	v_lshlrev_b32_e32 v170, 16, v171
	v_and_b32_e32 v171, 0xffff0000, v171
	v_fmac_f32_e32 v114, v126, v126
	v_fmac_f32_e32 v115, v128, v128
	v_pk_fma_f32 v[118:119], s[14:15], v[118:119], v[164:165]
	v_pk_fma_f32 v[164:165], s[26:27], v[116:117], v[170:171]
	v_add_f32_e32 v114, v114, v115
	v_mul_f32_e32 v115, v123, v123
	v_mul_f32_e32 v116, v125, v125
	v_fmac_f32_e32 v115, v122, v122
	v_fmac_f32_e32 v116, v124, v124
	v_add_f32_e32 v115, v115, v116
	v_add_f32_e32 v163, v114, v115
	v_cvt_pk_bf16_f32 v114, v126, v127
	v_cvt_pk_bf16_f32 v115, v128, v129
	v_cvt_pk_bf16_f32 v116, v122, v123
	v_cvt_pk_bf16_f32 v117, v124, v125
	global_store_dwordx4 v[156:157], v[114:117], off
	s_nop 1
	v_mul_f32_e32 v114, v119, v119
	v_mul_f32_e32 v115, v121, v121
	v_fmac_f32_e32 v114, v118, v118
	v_fmac_f32_e32 v115, v120, v120
	v_add_f32_e32 v114, v114, v115
	v_mul_f32_e32 v115, v167, v167
	v_mul_f32_e32 v116, v165, v165
	v_fmac_f32_e32 v115, v166, v166
	v_fmac_f32_e32 v116, v164, v164
	v_add_f32_e32 v115, v115, v116
	v_add_f32_e32 v114, v114, v115
	v_add_f32_e32 v122, v163, v114
	v_cvt_pk_bf16_f32 v114, v118, v119
	v_cvt_pk_bf16_f32 v115, v120, v121
	v_cvt_pk_bf16_f32 v116, v166, v167
	v_cvt_pk_bf16_f32 v117, v164, v165
	global_store_dwordx4 v[156:157], v[114:117], off offset:256
	s_nop 1
	v_mov_b32_e32 v114, v122
	s_nop 1
	v_permlane16_swap_b32_e32 v122, v114
	s_waitcnt lgkmcnt(0)
	v_add_f32_e32 v114, v122, v114
	s_nop 1
	v_mov_b32_e32 v115, v114
	s_nop 1
	v_permlane32_swap_b32_e32 v114, v115
	s_and_saveexec_b64 s[36:37], vcc
	s_cbranch_execz .LBB0_606
	s_waitcnt lgkmcnt(0)
	v_add_f32_e32 v116, v114, v115
	v_lshlrev_b64 v[114:115], 7, v[150:151]
	v_lshl_add_u64 v[114:115], s[24:25], 0, v[114:115]
	v_lshl_add_u64 v[114:115], s[34:35], 2, v[114:115]
	s_lshl_b32 s52, s77, 2
	v_lshl_add_u64 v[114:115], v[114:115], 0, s[52:53]
	global_store_dword v[114:115], v116, off
.LBB0_606:
	s_or_b64 exec, exec, s[36:37]
	v_or_b32_e32 v122, 32, v150
	v_ashrrev_i32_e32 v123, 31, v122
	s_waitcnt lgkmcnt(0)
	v_lshlrev_b64 v[114:115], 12, v[122:123]
	v_lshl_add_u64 v[114:115], s[22:23], 0, v[114:115]
	v_lshl_add_u64 v[124:125], v[148:149], 1, v[114:115]
	global_load_dwordx4 v[118:121], v[124:125], off
	global_load_dwordx4 v[114:117], v[124:125], off offset:256
	v_lshlrev_b32_e32 v126, 16, v134
	v_and_b32_e32 v127, 0xffff0000, v134
	v_lshlrev_b32_e32 v128, 16, v135
	v_and_b32_e32 v129, 0xffff0000, v135
	v_pk_fma_f32 v[112:113], s[26:27], v[112:113], v[128:129]
	v_pk_fma_f32 v[110:111], s[14:15], v[110:111], v[126:127]
	v_lshlrev_b32_e32 v126, 16, v130
	v_and_b32_e32 v127, 0xffff0000, v130
	v_lshlrev_b32_e32 v128, 16, v131
	v_and_b32_e32 v129, 0xffff0000, v131
	v_lshlrev_b32_e32 v130, 16, v132
	v_and_b32_e32 v131, 0xffff0000, v132
	v_lshlrev_b32_e32 v134, 16, v136
	v_and_b32_e32 v135, 0xffff0000, v136
	v_lshlrev_b32_e32 v136, 16, v137
	v_and_b32_e32 v137, 0xffff0000, v137
	v_pk_fma_f32 v[104:105], s[26:27], v[104:105], v[128:129]
	v_pk_fma_f32 v[128:129], s[14:15], v[98:99], v[130:131]
	v_mul_f32_e32 v98, v111, v111
	v_mul_f32_e32 v99, v113, v113
	v_pk_fma_f32 v[108:109], s[26:27], v[108:109], v[136:137]
	v_pk_fma_f32 v[106:107], s[14:15], v[106:107], v[134:135]
	v_lshlrev_b32_e32 v132, 16, v133
	v_and_b32_e32 v133, 0xffff0000, v133
	v_fmac_f32_e32 v98, v110, v110
	v_fmac_f32_e32 v99, v112, v112
	v_pk_fma_f32 v[102:103], s[14:15], v[102:103], v[126:127]
	v_pk_fma_f32 v[126:127], s[26:27], v[100:101], v[132:133]
	v_add_f32_e32 v98, v98, v99
	v_mul_f32_e32 v99, v107, v107
	v_mul_f32_e32 v100, v109, v109
	v_fmac_f32_e32 v99, v106, v106
	v_fmac_f32_e32 v100, v108, v108
	v_add_f32_e32 v99, v99, v100
	v_add_f32_e32 v100, v98, v99
	v_cvt_pk_bf16_f32 v98, v110, v111
	v_mul_f32_e32 v101, v103, v103
	v_mul_f32_e32 v110, v105, v105
	v_fmac_f32_e32 v101, v102, v102
	v_fmac_f32_e32 v110, v104, v104
	v_add_f32_e32 v101, v101, v110
	v_mul_f32_e32 v110, v129, v129
	v_mul_f32_e32 v111, v127, v127
	v_fmac_f32_e32 v110, v128, v128
	v_fmac_f32_e32 v111, v126, v126
	v_add_f32_e32 v110, v110, v111
	v_add_f32_e32 v101, v101, v110
	v_add_f32_e32 v110, v100, v101
	s_nop 1
	v_mov_b32_e32 v111, v110
	s_nop 1
	v_permlane16_swap_b32_e32 v110, v111
	v_cvt_pk_bf16_f32 v99, v112, v113
	v_cvt_pk_bf16_f32 v100, v106, v107
	v_cvt_pk_bf16_f32 v101, v108, v109
	global_store_dwordx4 v[154:155], v[98:101], off
	s_waitcnt lgkmcnt(0)
	s_nop 0
	v_add_f32_e32 v98, v110, v111
	s_nop 1
	v_mov_b32_e32 v99, v98
	s_nop 1
	v_permlane32_swap_b32_e32 v98, v99
	v_cvt_pk_bf16_f32 v100, v102, v103
	v_cvt_pk_bf16_f32 v101, v104, v105
	v_cvt_pk_bf16_f32 v102, v128, v129
	v_cvt_pk_bf16_f32 v103, v126, v127
	global_store_dwordx4 v[154:155], v[100:103], off offset:256
	s_and_saveexec_b64 s[36:37], vcc
	s_cbranch_execz .LBB0_608
; __device__ __forceinline__ unsigned cvt_pk_bf16(float lo, float hi) { unsigned r; asm volatile("v_cvt_pk_bf16_f32 %0, %1, %2" : "=v"(r) : "v"(lo), "v"(hi)); return r; }
; __device__ __forceinline__ void publish_row_p(const f32x4 (&xn)[2][2], bf16_t* xbrow, float* ssrow, int fq, int lane) {
;     ...
;     for (int bj = 0; bj < 2; ++bj) { const f32x4 v0 = xn[bj][0], v1 = xn[bj][1];
;         q += ((v0[0] * v0[0] + v0[1] * v0[1]) + (v0[2] * v0[2] + v0[3] * v0[3])) + ((v1[0] * v1[0] + v1[1] * v1[1]) + (v1[2] * v1[2] + v1[3] * v1[3]));
;         u32x4 w; w.x = cvt_pk_bf16(v0[0], v0[1]); w.y = cvt_pk_bf16(v0[2], v0[3]); w.z = cvt_pk_bf16(v1[0], v1[1]); w.w = cvt_pk_bf16(v1[2], v1[3]); *(u32x4*)(xbrow + bj * HALF) = w; }
;     q += __int_as_float(__builtin_amdgcn_ds_bpermute((lane ^ 16) << 2, __float_as_int(q)));
;     q += __int_as_float(__builtin_amdgcn_ds_bpermute((lane ^ 32) << 2, __float_as_int(q)));
;     if (fq == 0) *ssrow = q;
;     __device__ __forceinline__ void operator()(const f32x4 (&acc)[2][2][4][2], const Unit& u, int wr, int wc, int fr, int fq) const {
;     ...
;         for (int bj = 0; bj < 2; ++bj) xnext[bj] = *(const u32x4*)(S + (size_t)row0 * ldc + col0 + bj * HALF);
; #pragma unroll
;         for (int r = 0; r < 8; ++r) { const int ai = r >> 2, m = r & 3; const int row = row0 + ai * HALF + m * 16;
; #pragma unroll
;             for (int bj = 0; bj < 2; ++bj) xv[bj] = xnext[bj];
;             if (r < 7) { const int rown = row0 + ((r + 1) >> 2) * HALF + ((r + 1) & 3) * 16;
; #pragma unroll
;                 for (int bj = 0; bj < 2; ++bj) xnext[bj] = *(const u32x4*)(S + (size_t)rown * ldc + col0 + bj * HALF); }
;             f32x4 xn[2][2];
; #pragma unroll
;             for (int bj = 0; bj < 2; ++bj) { f32x4 a, b; unpack8(xv[bj], a, b); xn[bj][0] = a + acc[ai][bj][m][0] * alpha; xn[bj][1] = b + acc[ai][bj][m][1] * alpha; }
;             publish_row_p(xn, S + (size_t)row * ldc + col0, ss + (size_t)row * 32 + u.pn * 4 + wc, fq, lane); }
	s_waitcnt lgkmcnt(0)
	v_add_f32_e32 v100, v98, v99
	v_lshlrev_b64 v[98:99], 7, v[152:153]
	v_lshl_add_u64 v[98:99], s[24:25], 0, v[98:99]
	v_lshl_add_u64 v[98:99], s[34:35], 2, v[98:99]
	s_lshl_b32 s52, s77, 2
	v_lshl_add_u64 v[98:99], v[98:99], 0, s[52:53]
	global_store_dword v[98:99], v100, off
.LBB0_608:
	s_or_b64 exec, exec, s[36:37]
	v_or_b32_e32 v106, 48, v150
	v_ashrrev_i32_e32 v107, 31, v106
	s_waitcnt lgkmcnt(0)
	v_lshlrev_b64 v[98:99], 12, v[106:107]
	v_lshl_add_u64 v[98:99], s[22:23], 0, v[98:99]
	v_lshl_add_u64 v[108:109], v[148:149], 1, v[98:99]
	global_load_dwordx4 v[102:105], v[108:109], off
	global_load_dwordx4 v[98:101], v[108:109], off offset:256
	s_waitcnt vmcnt(5)
	v_lshlrev_b32_e32 v110, 16, v118
	v_and_b32_e32 v111, 0xffff0000, v118
	v_lshlrev_b32_e32 v112, 16, v119
	v_and_b32_e32 v113, 0xffff0000, v119
	v_pk_fma_f32 v[96:97], s[26:27], v[96:97], v[112:113]
	v_pk_fma_f32 v[94:95], s[14:15], v[94:95], v[110:111]
	s_waitcnt vmcnt(4)
	v_lshlrev_b32_e32 v110, 16, v114
	v_and_b32_e32 v111, 0xffff0000, v114
	v_lshlrev_b32_e32 v112, 16, v115
	v_and_b32_e32 v113, 0xffff0000, v115
	v_lshlrev_b32_e32 v114, 16, v116
	v_and_b32_e32 v115, 0xffff0000, v116
	v_lshlrev_b32_e32 v118, 16, v120
	v_and_b32_e32 v119, 0xffff0000, v120
	v_lshlrev_b32_e32 v120, 16, v121
	v_and_b32_e32 v121, 0xffff0000, v121
	v_pk_fma_f32 v[88:89], s[26:27], v[88:89], v[112:113]
	v_pk_fma_f32 v[112:113], s[14:15], v[82:83], v[114:115]
	v_mul_f32_e32 v82, v95, v95
	v_mul_f32_e32 v83, v97, v97
	v_pk_fma_f32 v[92:93], s[26:27], v[92:93], v[120:121]
	v_pk_fma_f32 v[90:91], s[14:15], v[90:91], v[118:119]
	v_lshlrev_b32_e32 v116, 16, v117
	v_and_b32_e32 v117, 0xffff0000, v117
	v_fmac_f32_e32 v82, v94, v94
	v_fmac_f32_e32 v83, v96, v96
	v_pk_fma_f32 v[86:87], s[14:15], v[86:87], v[110:111]
	v_pk_fma_f32 v[110:111], s[26:27], v[84:85], v[116:117]
	v_add_f32_e32 v82, v82, v83
	v_mul_f32_e32 v83, v91, v91
	v_mul_f32_e32 v84, v93, v93
	v_fmac_f32_e32 v83, v90, v90
	v_fmac_f32_e32 v84, v92, v92
	v_add_f32_e32 v83, v83, v84
	v_add_f32_e32 v84, v82, v83
	v_cvt_pk_bf16_f32 v82, v94, v95
	v_mul_f32_e32 v85, v87, v87
	v_mul_f32_e32 v94, v89, v89
	v_fmac_f32_e32 v85, v86, v86
	v_fmac_f32_e32 v94, v88, v88
	v_add_f32_e32 v85, v85, v94
	v_mul_f32_e32 v94, v113, v113
	v_mul_f32_e32 v95, v111, v111
	v_fmac_f32_e32 v94, v112, v112
	v_fmac_f32_e32 v95, v110, v110
	v_add_f32_e32 v94, v94, v95
	v_add_f32_e32 v85, v85, v94
	v_add_f32_e32 v94, v84, v85
	s_nop 1
	v_mov_b32_e32 v95, v94
	s_nop 1
	v_permlane16_swap_b32_e32 v94, v95
	v_cvt_pk_bf16_f32 v83, v96, v97
	v_cvt_pk_bf16_f32 v84, v90, v91
	v_cvt_pk_bf16_f32 v85, v92, v93
	global_store_dwordx4 v[124:125], v[82:85], off
	s_waitcnt lgkmcnt(0)
	s_nop 0
	v_add_f32_e32 v82, v94, v95
	s_nop 1
	v_mov_b32_e32 v83, v82
	s_nop 1
	v_permlane32_swap_b32_e32 v82, v83
	v_cvt_pk_bf16_f32 v84, v86, v87
	v_cvt_pk_bf16_f32 v85, v88, v89
	v_cvt_pk_bf16_f32 v86, v112, v113
	v_cvt_pk_bf16_f32 v87, v110, v111
	global_store_dwordx4 v[124:125], v[84:87], off offset:256
	s_and_saveexec_b64 s[36:37], vcc
	s_cbranch_execz .LBB0_610
	s_waitcnt lgkmcnt(0)
	v_add_f32_e32 v84, v82, v83
	v_lshlrev_b64 v[82:83], 7, v[122:123]
	v_lshl_add_u64 v[82:83], s[24:25], 0, v[82:83]
	v_lshl_add_u64 v[82:83], s[34:35], 2, v[82:83]
	s_lshl_b32 s52, s77, 2
	v_lshl_add_u64 v[82:83], v[82:83], 0, s[52:53]
	global_store_dword v[82:83], v84, off
.LBB0_610:
	s_or_b64 exec, exec, s[36:37]
	v_add_u32_e32 v90, 0x80, v150
	v_ashrrev_i32_e32 v91, 31, v90
	s_waitcnt lgkmcnt(0)
	v_lshlrev_b64 v[82:83], 12, v[90:91]
	v_lshl_add_u64 v[82:83], s[22:23], 0, v[82:83]
	v_lshl_add_u64 v[92:93], v[148:149], 1, v[82:83]
	global_load_dwordx4 v[86:89], v[92:93], off
	global_load_dwordx4 v[82:85], v[92:93], off offset:256
	s_waitcnt vmcnt(5)
	v_lshlrev_b32_e32 v94, 16, v102
	v_and_b32_e32 v95, 0xffff0000, v102
	v_lshlrev_b32_e32 v96, 16, v103
	v_and_b32_e32 v97, 0xffff0000, v103
	v_pk_fma_f32 v[80:81], s[26:27], v[80:81], v[96:97]
	v_pk_fma_f32 v[78:79], s[14:15], v[78:79], v[94:95]
	s_waitcnt vmcnt(4)
	v_lshlrev_b32_e32 v94, 16, v98
	v_and_b32_e32 v95, 0xffff0000, v98
	v_lshlrev_b32_e32 v96, 16, v99
	v_and_b32_e32 v97, 0xffff0000, v99
	v_lshlrev_b32_e32 v98, 16, v100
	v_and_b32_e32 v99, 0xffff0000, v100
	v_lshlrev_b32_e32 v102, 16, v104
	v_and_b32_e32 v103, 0xffff0000, v104
	v_lshlrev_b32_e32 v104, 16, v105
	v_and_b32_e32 v105, 0xffff0000, v105
	v_pk_fma_f32 v[72:73], s[26:27], v[72:73], v[96:97]
	v_pk_fma_f32 v[96:97], s[14:15], v[66:67], v[98:99]
	v_mul_f32_e32 v66, v79, v79
	v_mul_f32_e32 v67, v81, v81
	v_pk_fma_f32 v[76:77], s[26:27], v[76:77], v[104:105]
	v_pk_fma_f32 v[74:75], s[14:15], v[74:75], v[102:103]
	v_lshlrev_b32_e32 v100, 16, v101
	v_and_b32_e32 v101, 0xffff0000, v101
	v_fmac_f32_e32 v66, v78, v78
	v_fmac_f32_e32 v67, v80, v80
	v_pk_fma_f32 v[70:71], s[14:15], v[70:71], v[94:95]
	v_pk_fma_f32 v[94:95], s[26:27], v[68:69], v[100:101]
	v_add_f32_e32 v66, v66, v67
	v_mul_f32_e32 v67, v75, v75
	v_mul_f32_e32 v68, v77, v77
	v_fmac_f32_e32 v67, v74, v74
	v_fmac_f32_e32 v68, v76, v76
	v_add_f32_e32 v67, v67, v68
	v_add_f32_e32 v68, v66, v67
	v_cvt_pk_bf16_f32 v66, v78, v79
	v_mul_f32_e32 v69, v71, v71
	v_mul_f32_e32 v78, v73, v73
	v_fmac_f32_e32 v69, v70, v70
	v_fmac_f32_e32 v78, v72, v72
	v_add_f32_e32 v69, v69, v78
	v_mul_f32_e32 v78, v97, v97
	v_mul_f32_e32 v79, v95, v95
	v_fmac_f32_e32 v78, v96, v96
	v_fmac_f32_e32 v79, v94, v94
	v_add_f32_e32 v78, v78, v79
	v_add_f32_e32 v69, v69, v78
	v_add_f32_e32 v78, v68, v69
	s_nop 1
	v_mov_b32_e32 v79, v78
	s_nop 1
	v_permlane16_swap_b32_e32 v78, v79
	v_cvt_pk_bf16_f32 v67, v80, v81
	v_cvt_pk_bf16_f32 v68, v74, v75
	v_cvt_pk_bf16_f32 v69, v76, v77
	global_store_dwordx4 v[108:109], v[66:69], off
	s_waitcnt lgkmcnt(0)
	s_nop 0
	v_add_f32_e32 v66, v78, v79
	s_nop 1
	v_mov_b32_e32 v67, v66
	s_nop 1
	v_permlane32_swap_b32_e32 v66, v67
	v_cvt_pk_bf16_f32 v68, v70, v71
	v_cvt_pk_bf16_f32 v69, v72, v73
	v_cvt_pk_bf16_f32 v70, v96, v97
	v_cvt_pk_bf16_f32 v71, v94, v95
	global_store_dwordx4 v[108:109], v[68:71], off offset:256
	s_and_saveexec_b64 s[36:37], vcc
	s_cbranch_execz .LBB0_612
	s_waitcnt lgkmcnt(0)
	v_add_f32_e32 v68, v66, v67
	v_lshlrev_b64 v[66:67], 7, v[106:107]
	v_lshl_add_u64 v[66:67], s[24:25], 0, v[66:67]
	v_lshl_add_u64 v[66:67], s[34:35], 2, v[66:67]
	s_lshl_b32 s52, s77, 2
	v_lshl_add_u64 v[66:67], v[66:67], 0, s[52:53]
	global_store_dword v[66:67], v68, off
; __device__ __forceinline__ unsigned cvt_pk_bf16(float lo, float hi) { unsigned r; asm volatile("v_cvt_pk_bf16_f32 %0, %1, %2" : "=v"(r) : "v"(lo), "v"(hi)); return r; }
; __device__ __forceinline__ void publish_row_p(const f32x4 (&xn)[2][2], bf16_t* xbrow, float* ssrow, int fq, int lane) {
;     ...
;     for (int bj = 0; bj < 2; ++bj) { const f32x4 v0 = xn[bj][0], v1 = xn[bj][1];
;         q += ((v0[0] * v0[0] + v0[1] * v0[1]) + (v0[2] * v0[2] + v0[3] * v0[3])) + ((v1[0] * v1[0] + v1[1] * v1[1]) + (v1[2] * v1[2] + v1[3] * v1[3]));
;         u32x4 w; w.x = cvt_pk_bf16(v0[0], v0[1]); w.y = cvt_pk_bf16(v0[2], v0[3]); w.z = cvt_pk_bf16(v1[0], v1[1]); w.w = cvt_pk_bf16(v1[2], v1[3]); *(u32x4*)(xbrow + bj * HALF) = w; }
;     q += __int_as_float(__builtin_amdgcn_ds_bpermute((lane ^ 16) << 2, __float_as_int(q)));
;     q += __int_as_float(__builtin_amdgcn_ds_bpermute((lane ^ 32) << 2, __float_as_int(q)));
;     if (fq == 0) *ssrow = q;
;     __device__ __forceinline__ void operator()(const f32x4 (&acc)[2][2][4][2], const Unit& u, int wr, int wc, int fr, int fq) const {
;     ...
;         for (int bj = 0; bj < 2; ++bj) xnext[bj] = *(const u32x4*)(S + (size_t)row0 * ldc + col0 + bj * HALF);
; #pragma unroll
;         for (int r = 0; r < 8; ++r) { const int ai = r >> 2, m = r & 3; const int row = row0 + ai * HALF + m * 16;
; #pragma unroll
;             for (int bj = 0; bj < 2; ++bj) xv[bj] = xnext[bj];
;             if (r < 7) { const int rown = row0 + ((r + 1) >> 2) * HALF + ((r + 1) & 3) * 16;
; #pragma unroll
;                 for (int bj = 0; bj < 2; ++bj) xnext[bj] = *(const u32x4*)(S + (size_t)rown * ldc + col0 + bj * HALF); }
;             f32x4 xn[2][2];
; #pragma unroll
;             for (int bj = 0; bj < 2; ++bj) { f32x4 a, b; unpack8(xv[bj], a, b); xn[bj][0] = a + acc[ai][bj][m][0] * alpha; xn[bj][1] = b + acc[ai][bj][m][1] * alpha; }
;             publish_row_p(xn, S + (size_t)row * ldc + col0, ss + (size_t)row * 32 + u.pn * 4 + wc, fq, lane); }
.LBB0_612:
	s_or_b64 exec, exec, s[36:37]
	v_or_b32_e32 v74, 16, v90
	v_ashrrev_i32_e32 v75, 31, v74
	s_waitcnt lgkmcnt(0)
	v_lshlrev_b64 v[66:67], 12, v[74:75]
	v_lshl_add_u64 v[66:67], s[22:23], 0, v[66:67]
	v_lshl_add_u64 v[76:77], v[148:149], 1, v[66:67]
	global_load_dwordx4 v[70:73], v[76:77], off
	global_load_dwordx4 v[66:69], v[76:77], off offset:256
	s_waitcnt vmcnt(5)
	v_lshlrev_b32_e32 v78, 16, v86
	v_and_b32_e32 v79, 0xffff0000, v86
	v_lshlrev_b32_e32 v80, 16, v87
	v_and_b32_e32 v81, 0xffff0000, v87
	v_pk_fma_f32 v[64:65], s[26:27], v[64:65], v[80:81]
	v_pk_fma_f32 v[62:63], s[14:15], v[62:63], v[78:79]
	s_waitcnt vmcnt(4)
	v_lshlrev_b32_e32 v78, 16, v82
	v_and_b32_e32 v79, 0xffff0000, v82
	v_lshlrev_b32_e32 v80, 16, v83
	v_and_b32_e32 v81, 0xffff0000, v83
	v_lshlrev_b32_e32 v82, 16, v84
	v_and_b32_e32 v83, 0xffff0000, v84
	v_lshlrev_b32_e32 v86, 16, v88
	v_and_b32_e32 v87, 0xffff0000, v88
	v_lshlrev_b32_e32 v88, 16, v89
	v_and_b32_e32 v89, 0xffff0000, v89
	v_pk_fma_f32 v[56:57], s[26:27], v[56:57], v[80:81]
	v_pk_fma_f32 v[80:81], s[14:15], v[50:51], v[82:83]
	v_mul_f32_e32 v50, v63, v63
	v_mul_f32_e32 v51, v65, v65
	v_pk_fma_f32 v[60:61], s[26:27], v[60:61], v[88:89]
	v_pk_fma_f32 v[58:59], s[14:15], v[58:59], v[86:87]
	v_lshlrev_b32_e32 v84, 16, v85
	v_and_b32_e32 v85, 0xffff0000, v85
	v_fmac_f32_e32 v50, v62, v62
	v_fmac_f32_e32 v51, v64, v64
	v_pk_fma_f32 v[54:55], s[14:15], v[54:55], v[78:79]
	v_pk_fma_f32 v[78:79], s[26:27], v[52:53], v[84:85]
	v_add_f32_e32 v50, v50, v51
	v_mul_f32_e32 v51, v59, v59
	v_mul_f32_e32 v52, v61, v61
	v_fmac_f32_e32 v51, v58, v58
	v_fmac_f32_e32 v52, v60, v60
	v_add_f32_e32 v51, v51, v52
	v_add_f32_e32 v52, v50, v51
	v_cvt_pk_bf16_f32 v50, v62, v63
	v_mul_f32_e32 v53, v55, v55
	v_mul_f32_e32 v62, v57, v57
	v_fmac_f32_e32 v53, v54, v54
	v_fmac_f32_e32 v62, v56, v56
	v_add_f32_e32 v53, v53, v62
	v_mul_f32_e32 v62, v81, v81
	v_mul_f32_e32 v63, v79, v79
	v_fmac_f32_e32 v62, v80, v80
	v_fmac_f32_e32 v63, v78, v78
	v_add_f32_e32 v62, v62, v63
	v_add_f32_e32 v53, v53, v62
	v_add_f32_e32 v62, v52, v53
	s_nop 1
	v_mov_b32_e32 v63, v62
	s_nop 1
	v_permlane16_swap_b32_e32 v62, v63
	v_cvt_pk_bf16_f32 v51, v64, v65
	v_cvt_pk_bf16_f32 v52, v58, v59
	v_cvt_pk_bf16_f32 v53, v60, v61
	global_store_dwordx4 v[92:93], v[50:53], off
	s_waitcnt lgkmcnt(0)
	s_nop 0
	v_add_f32_e32 v50, v62, v63
	s_nop 1
	v_mov_b32_e32 v51, v50
	s_nop 1
	v_permlane32_swap_b32_e32 v50, v51
	v_cvt_pk_bf16_f32 v52, v54, v55
	v_cvt_pk_bf16_f32 v53, v56, v57
	v_cvt_pk_bf16_f32 v54, v80, v81
	v_cvt_pk_bf16_f32 v55, v78, v79
	global_store_dwordx4 v[92:93], v[52:55], off offset:256
	s_and_saveexec_b64 s[36:37], vcc
	s_cbranch_execz .LBB0_614
	s_waitcnt lgkmcnt(0)
	v_add_f32_e32 v52, v50, v51
	v_lshlrev_b64 v[50:51], 7, v[90:91]
	v_lshl_add_u64 v[50:51], s[24:25], 0, v[50:51]
	v_lshl_add_u64 v[50:51], s[34:35], 2, v[50:51]
	s_lshl_b32 s52, s77, 2
	v_lshl_add_u64 v[50:51], v[50:51], 0, s[52:53]
	global_store_dword v[50:51], v52, off
.LBB0_614:
	s_or_b64 exec, exec, s[36:37]
	v_or_b32_e32 v58, 32, v90
	v_ashrrev_i32_e32 v59, 31, v58
	s_waitcnt lgkmcnt(0)
	v_lshlrev_b64 v[50:51], 12, v[58:59]
	v_lshl_add_u64 v[50:51], s[22:23], 0, v[50:51]
	v_lshl_add_u64 v[60:61], v[148:149], 1, v[50:51]
	global_load_dwordx4 v[54:57], v[60:61], off
	global_load_dwordx4 v[50:53], v[60:61], off offset:256
	s_waitcnt vmcnt(5)
	v_lshlrev_b32_e32 v62, 16, v70
	v_and_b32_e32 v63, 0xffff0000, v70
	v_lshlrev_b32_e32 v64, 16, v71
	v_and_b32_e32 v65, 0xffff0000, v71
	v_pk_fma_f32 v[48:49], s[26:27], v[48:49], v[64:65]
	v_pk_fma_f32 v[46:47], s[14:15], v[46:47], v[62:63]
	s_waitcnt vmcnt(4)
	v_lshlrev_b32_e32 v62, 16, v66
	v_and_b32_e32 v63, 0xffff0000, v66
	v_lshlrev_b32_e32 v64, 16, v67
	v_and_b32_e32 v65, 0xffff0000, v67
	v_lshlrev_b32_e32 v66, 16, v68
	v_and_b32_e32 v67, 0xffff0000, v68
	v_lshlrev_b32_e32 v70, 16, v72
	v_and_b32_e32 v71, 0xffff0000, v72
	v_lshlrev_b32_e32 v72, 16, v73
	v_and_b32_e32 v73, 0xffff0000, v73
	v_pk_fma_f32 v[40:41], s[26:27], v[40:41], v[64:65]
	v_pk_fma_f32 v[64:65], s[14:15], v[34:35], v[66:67]
	v_mul_f32_e32 v34, v47, v47
	v_mul_f32_e32 v35, v49, v49
	v_pk_fma_f32 v[44:45], s[26:27], v[44:45], v[72:73]
	v_pk_fma_f32 v[42:43], s[14:15], v[42:43], v[70:71]
	v_lshlrev_b32_e32 v68, 16, v69
	v_and_b32_e32 v69, 0xffff0000, v69
	v_fmac_f32_e32 v34, v46, v46
	v_fmac_f32_e32 v35, v48, v48
	v_pk_fma_f32 v[38:39], s[14:15], v[38:39], v[62:63]
	v_pk_fma_f32 v[62:63], s[26:27], v[36:37], v[68:69]
	v_add_f32_e32 v34, v34, v35
	v_mul_f32_e32 v35, v43, v43
	v_mul_f32_e32 v36, v45, v45
	v_fmac_f32_e32 v35, v42, v42
	v_fmac_f32_e32 v36, v44, v44
	v_add_f32_e32 v35, v35, v36
	v_add_f32_e32 v36, v34, v35
	v_cvt_pk_bf16_f32 v34, v46, v47
	v_mul_f32_e32 v37, v39, v39
	v_mul_f32_e32 v46, v41, v41
	v_fmac_f32_e32 v37, v38, v38
	v_fmac_f32_e32 v46, v40, v40
	v_add_f32_e32 v37, v37, v46
	v_mul_f32_e32 v46, v65, v65
	v_mul_f32_e32 v47, v63, v63
	v_fmac_f32_e32 v46, v64, v64
	v_fmac_f32_e32 v47, v62, v62
	v_add_f32_e32 v46, v46, v47
	v_add_f32_e32 v37, v37, v46
	v_add_f32_e32 v46, v36, v37
	s_nop 1
	v_mov_b32_e32 v47, v46
	s_nop 1
	v_permlane16_swap_b32_e32 v46, v47
	v_cvt_pk_bf16_f32 v35, v48, v49
	v_cvt_pk_bf16_f32 v36, v42, v43
	v_cvt_pk_bf16_f32 v37, v44, v45
	global_store_dwordx4 v[76:77], v[34:37], off
	s_waitcnt lgkmcnt(0)
	s_nop 0
	v_add_f32_e32 v34, v46, v47
	s_nop 1
	v_mov_b32_e32 v35, v34
	s_nop 1
	v_permlane32_swap_b32_e32 v34, v35
	v_cvt_pk_bf16_f32 v36, v38, v39
	v_cvt_pk_bf16_f32 v37, v40, v41
	v_cvt_pk_bf16_f32 v38, v64, v65
	v_cvt_pk_bf16_f32 v39, v62, v63
	global_store_dwordx4 v[76:77], v[36:39], off offset:256
	s_and_saveexec_b64 s[36:37], vcc
	s_cbranch_execz .LBB0_616
	s_waitcnt lgkmcnt(0)
	v_add_f32_e32 v36, v34, v35
	v_lshlrev_b64 v[34:35], 7, v[74:75]
	v_lshl_add_u64 v[34:35], s[24:25], 0, v[34:35]
	v_lshl_add_u64 v[34:35], s[34:35], 2, v[34:35]
	s_lshl_b32 s52, s77, 2
	v_lshl_add_u64 v[34:35], v[34:35], 0, s[52:53]
	global_store_dword v[34:35], v36, off
; __device__ __forceinline__ unsigned cvt_pk_bf16(float lo, float hi) { unsigned r; asm volatile("v_cvt_pk_bf16_f32 %0, %1, %2" : "=v"(r) : "v"(lo), "v"(hi)); return r; }
; __device__ __forceinline__ void publish_row_p(const f32x4 (&xn)[2][2], bf16_t* xbrow, float* ssrow, int fq, int lane) {
;     ...
;     for (int bj = 0; bj < 2; ++bj) { const f32x4 v0 = xn[bj][0], v1 = xn[bj][1];
;         q += ((v0[0] * v0[0] + v0[1] * v0[1]) + (v0[2] * v0[2] + v0[3] * v0[3])) + ((v1[0] * v1[0] + v1[1] * v1[1]) + (v1[2] * v1[2] + v1[3] * v1[3]));
;         u32x4 w; w.x = cvt_pk_bf16(v0[0], v0[1]); w.y = cvt_pk_bf16(v0[2], v0[3]); w.z = cvt_pk_bf16(v1[0], v1[1]); w.w = cvt_pk_bf16(v1[2], v1[3]); *(u32x4*)(xbrow + bj * HALF) = w; }
;     q += __int_as_float(__builtin_amdgcn_ds_bpermute((lane ^ 16) << 2, __float_as_int(q)));
;     q += __int_as_float(__builtin_amdgcn_ds_bpermute((lane ^ 32) << 2, __float_as_int(q)));
;     if (fq == 0) *ssrow = q;
;     __device__ __forceinline__ void operator()(const f32x4 (&acc)[2][2][4][2], const Unit& u, int wr, int wc, int fr, int fq) const {
;     ...
;         for (int bj = 0; bj < 2; ++bj) xnext[bj] = *(const u32x4*)(S + (size_t)row0 * ldc + col0 + bj * HALF);
; #pragma unroll
;         for (int r = 0; r < 8; ++r) { const int ai = r >> 2, m = r & 3; const int row = row0 + ai * HALF + m * 16;
; #pragma unroll
;             for (int bj = 0; bj < 2; ++bj) xv[bj] = xnext[bj];
;             if (r < 7) { const int rown = row0 + ((r + 1) >> 2) * HALF + ((r + 1) & 3) * 16;
; #pragma unroll
;                 for (int bj = 0; bj < 2; ++bj) xnext[bj] = *(const u32x4*)(S + (size_t)rown * ldc + col0 + bj * HALF); }
;             f32x4 xn[2][2];
; #pragma unroll
;             for (int bj = 0; bj < 2; ++bj) { f32x4 a, b; unpack8(xv[bj], a, b); xn[bj][0] = a + acc[ai][bj][m][0] * alpha; xn[bj][1] = b + acc[ai][bj][m][1] * alpha; }
;             publish_row_p(xn, S + (size_t)row * ldc + col0, ss + (size_t)row * 32 + u.pn * 4 + wc, fq, lane); }
.LBB0_616:
	s_or_b64 exec, exec, s[36:37]
	v_or_b32_e32 v42, 48, v90
	v_ashrrev_i32_e32 v43, 31, v42
	s_waitcnt lgkmcnt(0)
	v_lshlrev_b64 v[34:35], 12, v[42:43]
	v_lshl_add_u64 v[34:35], s[22:23], 0, v[34:35]
	v_lshl_add_u64 v[44:45], v[148:149], 1, v[34:35]
	global_load_dwordx4 v[38:41], v[44:45], off
	global_load_dwordx4 v[34:37], v[44:45], off offset:256
	s_waitcnt vmcnt(5)
	v_lshlrev_b32_e32 v46, 16, v54
	v_and_b32_e32 v47, 0xffff0000, v54
	v_lshlrev_b32_e32 v48, 16, v55
	v_and_b32_e32 v49, 0xffff0000, v55
	v_pk_fma_f32 v[32:33], s[26:27], v[32:33], v[48:49]
	v_pk_fma_f32 v[30:31], s[14:15], v[30:31], v[46:47]
	s_waitcnt vmcnt(4)
	v_lshlrev_b32_e32 v46, 16, v50
	v_and_b32_e32 v47, 0xffff0000, v50
	v_lshlrev_b32_e32 v48, 16, v51
	v_and_b32_e32 v49, 0xffff0000, v51
	v_lshlrev_b32_e32 v50, 16, v52
	v_and_b32_e32 v51, 0xffff0000, v52
	v_lshlrev_b32_e32 v54, 16, v56
	v_and_b32_e32 v55, 0xffff0000, v56
	v_lshlrev_b32_e32 v56, 16, v57
	v_and_b32_e32 v57, 0xffff0000, v57
	v_pk_fma_f32 v[24:25], s[26:27], v[24:25], v[48:49]
	v_pk_fma_f32 v[48:49], s[14:15], v[18:19], v[50:51]
	v_mul_f32_e32 v18, v31, v31
	v_mul_f32_e32 v19, v33, v33
	v_pk_fma_f32 v[28:29], s[26:27], v[28:29], v[56:57]
	v_pk_fma_f32 v[26:27], s[14:15], v[26:27], v[54:55]
	v_lshlrev_b32_e32 v52, 16, v53
	v_and_b32_e32 v53, 0xffff0000, v53
	v_fmac_f32_e32 v18, v30, v30
	v_fmac_f32_e32 v19, v32, v32
	v_pk_fma_f32 v[22:23], s[14:15], v[22:23], v[46:47]
	v_pk_fma_f32 v[46:47], s[26:27], v[20:21], v[52:53]
	v_add_f32_e32 v18, v18, v19
	v_mul_f32_e32 v19, v27, v27
	v_mul_f32_e32 v20, v29, v29
	v_fmac_f32_e32 v19, v26, v26
	v_fmac_f32_e32 v20, v28, v28
	v_add_f32_e32 v19, v19, v20
	v_add_f32_e32 v20, v18, v19
	v_cvt_pk_bf16_f32 v18, v30, v31
	v_mul_f32_e32 v21, v23, v23
	v_mul_f32_e32 v30, v25, v25
	v_fmac_f32_e32 v21, v22, v22
	v_fmac_f32_e32 v30, v24, v24
	v_add_f32_e32 v21, v21, v30
	v_mul_f32_e32 v30, v49, v49
	v_mul_f32_e32 v31, v47, v47
	v_fmac_f32_e32 v30, v48, v48
	v_fmac_f32_e32 v31, v46, v46
	v_add_f32_e32 v30, v30, v31
	v_add_f32_e32 v21, v21, v30
	v_add_f32_e32 v30, v20, v21
	s_nop 1
	v_mov_b32_e32 v31, v30
	s_nop 1
	v_permlane16_swap_b32_e32 v30, v31
	v_cvt_pk_bf16_f32 v19, v32, v33
	v_cvt_pk_bf16_f32 v20, v26, v27
	v_cvt_pk_bf16_f32 v21, v28, v29
	global_store_dwordx4 v[60:61], v[18:21], off
	s_waitcnt lgkmcnt(0)
	s_nop 0
	v_add_f32_e32 v18, v30, v31
	s_nop 1
	v_mov_b32_e32 v19, v18
	s_nop 1
	v_permlane32_swap_b32_e32 v18, v19
	v_cvt_pk_bf16_f32 v20, v22, v23
	v_cvt_pk_bf16_f32 v21, v24, v25
	v_cvt_pk_bf16_f32 v22, v48, v49
	v_cvt_pk_bf16_f32 v23, v46, v47
	global_store_dwordx4 v[60:61], v[20:23], off offset:256
	s_and_saveexec_b64 s[36:37], vcc
	s_cbranch_execz .LBB0_618
	s_waitcnt lgkmcnt(0)
	v_add_f32_e32 v20, v18, v19
	v_lshlrev_b64 v[18:19], 7, v[58:59]
	v_lshl_add_u64 v[18:19], s[24:25], 0, v[18:19]
	v_lshl_add_u64 v[18:19], s[34:35], 2, v[18:19]
	s_lshl_b32 s52, s77, 2
	v_lshl_add_u64 v[18:19], v[18:19], 0, s[52:53]
	global_store_dword v[18:19], v20, off
.LBB0_618:
	s_or_b64 exec, exec, s[36:37]
	s_waitcnt vmcnt(3)
	v_lshlrev_b32_e32 v18, 16, v38
	s_waitcnt lgkmcnt(0)
	v_and_b32_e32 v19, 0xffff0000, v38
	v_lshlrev_b32_e32 v20, 16, v39
	v_and_b32_e32 v21, 0xffff0000, v39
	v_lshlrev_b32_e32 v22, 16, v40
	v_and_b32_e32 v23, 0xffff0000, v40
	v_pk_fma_f32 v[16:17], s[26:27], v[16:17], v[20:21]
	v_pk_fma_f32 v[14:15], s[14:15], v[14:15], v[18:19]
	v_pk_fma_f32 v[10:11], s[14:15], v[10:11], v[22:23]
	s_waitcnt vmcnt(2)
	v_lshlrev_b32_e32 v20, 16, v35
	v_and_b32_e32 v21, 0xffff0000, v35
	v_lshlrev_b32_e32 v22, 16, v36
	v_and_b32_e32 v23, 0xffff0000, v36
	v_lshlrev_b32_e32 v24, 16, v41
	v_and_b32_e32 v25, 0xffff0000, v41
	v_pk_fma_f32 v[8:9], s[26:27], v[8:9], v[20:21]
	v_pk_fma_f32 v[20:21], s[14:15], v[2:3], v[22:23]
	v_mul_f32_e32 v2, v15, v15
	v_mul_f32_e32 v3, v17, v17
	v_pk_fma_f32 v[12:13], s[26:27], v[12:13], v[24:25]
	v_lshlrev_b32_e32 v18, 16, v34
	v_and_b32_e32 v19, 0xffff0000, v34
	v_lshlrev_b32_e32 v24, 16, v37
	v_and_b32_e32 v25, 0xffff0000, v37
	v_fmac_f32_e32 v2, v14, v14
	v_fmac_f32_e32 v3, v16, v16
	v_pk_fma_f32 v[6:7], s[14:15], v[6:7], v[18:19]
	v_pk_fma_f32 v[18:19], s[26:27], v[4:5], v[24:25]
	v_add_f32_e32 v2, v2, v3
	v_mul_f32_e32 v3, v11, v11
	v_mul_f32_e32 v4, v13, v13
	v_fmac_f32_e32 v3, v10, v10
	v_fmac_f32_e32 v4, v12, v12
	v_add_f32_e32 v3, v3, v4
	v_add_f32_e32 v4, v2, v3
	v_cvt_pk_bf16_f32 v2, v14, v15
	v_mul_f32_e32 v5, v7, v7
	v_mul_f32_e32 v14, v9, v9
	v_fmac_f32_e32 v5, v6, v6
	v_fmac_f32_e32 v14, v8, v8
	v_add_f32_e32 v5, v5, v14
	v_mul_f32_e32 v14, v21, v21
	v_mul_f32_e32 v15, v19, v19
	v_fmac_f32_e32 v14, v20, v20
	v_fmac_f32_e32 v15, v18, v18
	v_add_f32_e32 v14, v14, v15
	v_add_f32_e32 v5, v5, v14
	v_add_f32_e32 v14, v4, v5
	s_nop 1
	v_mov_b32_e32 v15, v14
	s_nop 1
	v_permlane16_swap_b32_e32 v14, v15
	v_cvt_pk_bf16_f32 v3, v16, v17
	v_cvt_pk_bf16_f32 v4, v10, v11
	v_cvt_pk_bf16_f32 v5, v12, v13
	global_store_dwordx4 v[44:45], v[2:5], off
	s_waitcnt lgkmcnt(0)
	s_nop 0
	v_add_f32_e32 v2, v14, v15
	s_nop 1
	v_mov_b32_e32 v3, v2
	s_nop 1
	v_permlane32_swap_b32_e32 v2, v3
	v_cvt_pk_bf16_f32 v4, v6, v7
	v_cvt_pk_bf16_f32 v5, v8, v9
	v_cvt_pk_bf16_f32 v6, v20, v21
	v_cvt_pk_bf16_f32 v7, v18, v19
	global_store_dwordx4 v[44:45], v[4:7], off offset:256
	s_and_saveexec_b64 s[36:37], vcc
	s_cbranch_execz .LBB0_620
	s_waitcnt lgkmcnt(0)
	v_add_f32_e32 v4, v2, v3
	v_lshlrev_b64 v[2:3], 7, v[42:43]
	v_lshl_add_u64 v[2:3], s[24:25], 0, v[2:3]
	v_lshl_add_u64 v[2:3], s[34:35], 2, v[2:3]
	s_lshl_b32 s52, s77, 2
	v_lshl_add_u64 v[2:3], v[2:3], 0, s[52:53]
	global_store_dword v[2:3], v4, off
